# EpiResid epilogues: one counted vmcnt per full-line load (first consumer) instead of one wait per 8-load chunk
# speedup vs baseline: 1.0121x; 1.0018x over previous
;     __device__ __forceinline__ void operator()(const f32x4 (&acc)[2][2][4][2], const Unit& u, int wr, int wc, int fr, int fq) const {
;         int row0 = u.pm * BM + wr * 64 + fr, col0 = u.pn * BM + wc * 32 + 4 * fq;
;         asm volatile("" : "+v"(row0), "+v"(col0));
;         f32x4 b[2][2][2][2];
; #pragma unroll
;         for (int ch = 0; ch <= 4; ++ch) {
;             if (ch < 4) {
; #pragma unroll
;                 for (int mm = 0; mm < 2; ++mm) { const size_t off = (size_t)(row0 + (ch >> 1) * HALF + ((ch & 1) * 2 + mm) * 16) * ldc + col0;
; #pragma unroll
;                     for (int bj = 0; bj < 2; ++bj)
; #pragma unroll
;                         for (int n = 0; n < 2; ++n) b[ch & 1][mm][bj][n] = *(const f32x4*)(base + off + bj * HALF + n * 16); }
.LBB0_198:
	s_and_b64 vcc, exec, s[0:1]
	v_bfe_u32 v227, v214, 3, 1
	v_and_b32_e32 v228, 0x77, v214
	v_lshl_add_u32 v229, v227, 4, v215
	v_lshl_add_u32 v225, s36, 8, v228
	v_lshl_or_b32 v226, s37, 8, v229
	v_lshlrev_b32_e32 v224, 13, v225
	v_lshl_add_u32 v224, v226, 2, v224
	v_xor_b32_e32 v230, 16, v188
	v_xor_b32_e32 v231, 32, v188
	v_lshlrev_b32_e32 v230, 2, v230
	v_lshlrev_b32_e32 v231, 2, v231
	v_cmp_ne_u32_e64 s[62:63], 0, v227
	v_lshl_add_u32 v232, s36, 8, v214
	v_lshlrev_b32_e32 v232, 7, v232
	v_bfe_u32 v233, v215, 5, 2
	v_lshl_add_u32 v233, s37, 2, v233
	v_lshl_add_u32 v232, v233, 2, v232
	v_lshrrev_b32_e32 v234, 1, v224
	v_readlane_b32 s60, v254, 7
	v_readlane_b32 s61, v254, 8
	v_readlane_b32 s36, v254, 44
	v_readlane_b32 s37, v254, 45
	v_readlane_b32 s48, v255, 10
	v_readlane_b32 s49, v255, 11
	s_nop 7
	v_mov_b32_e32 v132, v144
	v_mov_b32_e32 v133, v145
	v_mov_b32_e32 v134, v146
	v_mov_b32_e32 v135, v147
	v_mov_b32_dpp v144, v160 row_ror:8 row_mask:0xf bank_mask:0x3
	v_mov_b32_dpp v145, v161 row_ror:8 row_mask:0xf bank_mask:0x3
	v_mov_b32_dpp v146, v162 row_ror:8 row_mask:0xf bank_mask:0x3
	v_mov_b32_dpp v147, v163 row_ror:8 row_mask:0xf bank_mask:0x3
	v_mov_b32_dpp v160, v132 row_ror:8 row_mask:0xf bank_mask:0xc
	v_mov_b32_dpp v161, v133 row_ror:8 row_mask:0xf bank_mask:0xc
	v_mov_b32_dpp v162, v134 row_ror:8 row_mask:0xf bank_mask:0xc
	v_mov_b32_dpp v163, v135 row_ror:8 row_mask:0xf bank_mask:0xc
	v_mov_b32_e32 v132, v128
	v_mov_b32_e32 v133, v129
	v_mov_b32_e32 v134, v130
	v_mov_b32_e32 v135, v131
	v_mov_b32_dpp v128, v136 row_ror:8 row_mask:0xf bank_mask:0x3
	v_mov_b32_dpp v129, v137 row_ror:8 row_mask:0xf bank_mask:0x3
	v_mov_b32_dpp v130, v138 row_ror:8 row_mask:0xf bank_mask:0x3
	v_mov_b32_dpp v131, v139 row_ror:8 row_mask:0xf bank_mask:0x3
	v_mov_b32_dpp v136, v132 row_ror:8 row_mask:0xf bank_mask:0xc
	v_mov_b32_dpp v137, v133 row_ror:8 row_mask:0xf bank_mask:0xc
	v_mov_b32_dpp v138, v134 row_ror:8 row_mask:0xf bank_mask:0xc
	v_mov_b32_dpp v139, v135 row_ror:8 row_mask:0xf bank_mask:0xc
	v_mov_b32_e32 v132, v104
	v_mov_b32_e32 v133, v105
	v_mov_b32_e32 v134, v106
	v_mov_b32_e32 v135, v107
	v_mov_b32_dpp v104, v108 row_ror:8 row_mask:0xf bank_mask:0x3
	v_mov_b32_dpp v105, v109 row_ror:8 row_mask:0xf bank_mask:0x3
	v_mov_b32_dpp v106, v110 row_ror:8 row_mask:0xf bank_mask:0x3
	v_mov_b32_dpp v107, v111 row_ror:8 row_mask:0xf bank_mask:0x3
	v_mov_b32_dpp v108, v132 row_ror:8 row_mask:0xf bank_mask:0xc
	v_mov_b32_dpp v109, v133 row_ror:8 row_mask:0xf bank_mask:0xc
	v_mov_b32_dpp v110, v134 row_ror:8 row_mask:0xf bank_mask:0xc
	v_mov_b32_dpp v111, v135 row_ror:8 row_mask:0xf bank_mask:0xc
	v_mov_b32_e32 v132, v96
	v_mov_b32_e32 v133, v97
	v_mov_b32_e32 v134, v98
	v_mov_b32_e32 v135, v99
	v_mov_b32_dpp v96, v100 row_ror:8 row_mask:0xf bank_mask:0x3
	v_mov_b32_dpp v97, v101 row_ror:8 row_mask:0xf bank_mask:0x3
	v_mov_b32_dpp v98, v102 row_ror:8 row_mask:0xf bank_mask:0x3
	v_mov_b32_dpp v99, v103 row_ror:8 row_mask:0xf bank_mask:0x3
	v_mov_b32_dpp v100, v132 row_ror:8 row_mask:0xf bank_mask:0xc
	v_mov_b32_dpp v101, v133 row_ror:8 row_mask:0xf bank_mask:0xc
	v_mov_b32_dpp v102, v134 row_ror:8 row_mask:0xf bank_mask:0xc
	v_mov_b32_dpp v103, v135 row_ror:8 row_mask:0xf bank_mask:0xc
	v_mov_b32_e32 v132, v88
	v_mov_b32_e32 v133, v89
	v_mov_b32_e32 v134, v90
	v_mov_b32_e32 v135, v91
	v_mov_b32_dpp v88, v92 row_ror:8 row_mask:0xf bank_mask:0x3
	v_mov_b32_dpp v89, v93 row_ror:8 row_mask:0xf bank_mask:0x3
	v_mov_b32_dpp v90, v94 row_ror:8 row_mask:0xf bank_mask:0x3
	v_mov_b32_dpp v91, v95 row_ror:8 row_mask:0xf bank_mask:0x3
	v_mov_b32_dpp v92, v132 row_ror:8 row_mask:0xf bank_mask:0xc
	v_mov_b32_dpp v93, v133 row_ror:8 row_mask:0xf bank_mask:0xc
	v_mov_b32_dpp v94, v134 row_ror:8 row_mask:0xf bank_mask:0xc
	v_mov_b32_dpp v95, v135 row_ror:8 row_mask:0xf bank_mask:0xc
	v_mov_b32_e32 v132, v80
	v_mov_b32_e32 v133, v81
	v_mov_b32_e32 v134, v82
	v_mov_b32_e32 v135, v83
	v_mov_b32_dpp v80, v84 row_ror:8 row_mask:0xf bank_mask:0x3
	v_mov_b32_dpp v81, v85 row_ror:8 row_mask:0xf bank_mask:0x3
	v_mov_b32_dpp v82, v86 row_ror:8 row_mask:0xf bank_mask:0x3
	v_mov_b32_dpp v83, v87 row_ror:8 row_mask:0xf bank_mask:0x3
	v_mov_b32_dpp v84, v132 row_ror:8 row_mask:0xf bank_mask:0xc
	v_mov_b32_dpp v85, v133 row_ror:8 row_mask:0xf bank_mask:0xc
	v_mov_b32_dpp v86, v134 row_ror:8 row_mask:0xf bank_mask:0xc
	v_mov_b32_dpp v87, v135 row_ror:8 row_mask:0xf bank_mask:0xc
	v_mov_b32_e32 v132, v72
	v_mov_b32_e32 v133, v73
	v_mov_b32_e32 v134, v74
	v_mov_b32_e32 v135, v75
	v_mov_b32_dpp v72, v76 row_ror:8 row_mask:0xf bank_mask:0x3
	v_mov_b32_dpp v73, v77 row_ror:8 row_mask:0xf bank_mask:0x3
	v_mov_b32_dpp v74, v78 row_ror:8 row_mask:0xf bank_mask:0x3
	v_mov_b32_dpp v75, v79 row_ror:8 row_mask:0xf bank_mask:0x3
	v_mov_b32_dpp v76, v132 row_ror:8 row_mask:0xf bank_mask:0xc
	v_mov_b32_dpp v77, v133 row_ror:8 row_mask:0xf bank_mask:0xc
	v_mov_b32_dpp v78, v134 row_ror:8 row_mask:0xf bank_mask:0xc
	v_mov_b32_dpp v79, v135 row_ror:8 row_mask:0xf bank_mask:0xc
	v_mov_b32_e32 v132, v64
	v_mov_b32_e32 v133, v65
	v_mov_b32_e32 v134, v66
	v_mov_b32_e32 v135, v67
	v_mov_b32_dpp v64, v68 row_ror:8 row_mask:0xf bank_mask:0x3
	v_mov_b32_dpp v65, v69 row_ror:8 row_mask:0xf bank_mask:0x3
	v_mov_b32_dpp v66, v70 row_ror:8 row_mask:0xf bank_mask:0x3
	v_mov_b32_dpp v67, v71 row_ror:8 row_mask:0xf bank_mask:0x3
	v_mov_b32_dpp v68, v132 row_ror:8 row_mask:0xf bank_mask:0xc
	v_mov_b32_dpp v69, v133 row_ror:8 row_mask:0xf bank_mask:0xc
	v_mov_b32_dpp v70, v134 row_ror:8 row_mask:0xf bank_mask:0xc
	v_mov_b32_dpp v71, v135 row_ror:8 row_mask:0xf bank_mask:0xc
	v_mov_b32_e32 v132, v56
;     __device__ __forceinline__ void operator()(const f32x4 (&acc)[2][2][4][2], const Unit& u, int wr, int wc, int fr, int fq) const {
;         int row0 = u.pm * BM + wr * 64 + fr, col0 = u.pn * BM + wc * 32 + 4 * fq;
;         asm volatile("" : "+v"(row0), "+v"(col0));
;         f32x4 b[2][2][2][2];
; #pragma unroll
;         for (int ch = 0; ch <= 4; ++ch) {
;             if (ch < 4) {
; #pragma unroll
;                 for (int mm = 0; mm < 2; ++mm) { const size_t off = (size_t)(row0 + (ch >> 1) * HALF + ((ch & 1) * 2 + mm) * 16) * ldc + col0;
; #pragma unroll
;                     for (int bj = 0; bj < 2; ++bj)
; #pragma unroll
;                         for (int n = 0; n < 2; ++n) b[ch & 1][mm][bj][n] = *(const f32x4*)(base + off + bj * HALF + n * 16); }
	v_mov_b32_e32 v133, v57
	v_mov_b32_e32 v134, v58
	v_mov_b32_e32 v135, v59
	v_mov_b32_dpp v56, v60 row_ror:8 row_mask:0xf bank_mask:0x3
	v_mov_b32_dpp v57, v61 row_ror:8 row_mask:0xf bank_mask:0x3
	v_mov_b32_dpp v58, v62 row_ror:8 row_mask:0xf bank_mask:0x3
	v_mov_b32_dpp v59, v63 row_ror:8 row_mask:0xf bank_mask:0x3
	v_mov_b32_dpp v60, v132 row_ror:8 row_mask:0xf bank_mask:0xc
	v_mov_b32_dpp v61, v133 row_ror:8 row_mask:0xf bank_mask:0xc
	v_mov_b32_dpp v62, v134 row_ror:8 row_mask:0xf bank_mask:0xc
	v_mov_b32_dpp v63, v135 row_ror:8 row_mask:0xf bank_mask:0xc
	v_mov_b32_e32 v132, v48
	v_mov_b32_e32 v133, v49
	v_mov_b32_e32 v134, v50
	v_mov_b32_e32 v135, v51
	v_mov_b32_dpp v48, v52 row_ror:8 row_mask:0xf bank_mask:0x3
	v_mov_b32_dpp v49, v53 row_ror:8 row_mask:0xf bank_mask:0x3
	v_mov_b32_dpp v50, v54 row_ror:8 row_mask:0xf bank_mask:0x3
	v_mov_b32_dpp v51, v55 row_ror:8 row_mask:0xf bank_mask:0x3
	v_mov_b32_dpp v52, v132 row_ror:8 row_mask:0xf bank_mask:0xc
	v_mov_b32_dpp v53, v133 row_ror:8 row_mask:0xf bank_mask:0xc
	v_mov_b32_dpp v54, v134 row_ror:8 row_mask:0xf bank_mask:0xc
	v_mov_b32_dpp v55, v135 row_ror:8 row_mask:0xf bank_mask:0xc
	v_mov_b32_e32 v132, v40
	v_mov_b32_e32 v133, v41
	v_mov_b32_e32 v134, v42
	v_mov_b32_e32 v135, v43
	v_mov_b32_dpp v40, v44 row_ror:8 row_mask:0xf bank_mask:0x3
	v_mov_b32_dpp v41, v45 row_ror:8 row_mask:0xf bank_mask:0x3
	v_mov_b32_dpp v42, v46 row_ror:8 row_mask:0xf bank_mask:0x3
	v_mov_b32_dpp v43, v47 row_ror:8 row_mask:0xf bank_mask:0x3
	v_mov_b32_dpp v44, v132 row_ror:8 row_mask:0xf bank_mask:0xc
	v_mov_b32_dpp v45, v133 row_ror:8 row_mask:0xf bank_mask:0xc
	v_mov_b32_dpp v46, v134 row_ror:8 row_mask:0xf bank_mask:0xc
	v_mov_b32_dpp v47, v135 row_ror:8 row_mask:0xf bank_mask:0xc
	v_mov_b32_e32 v132, v32
	v_mov_b32_e32 v133, v33
	v_mov_b32_e32 v134, v34
	v_mov_b32_e32 v135, v35
	v_mov_b32_dpp v32, v36 row_ror:8 row_mask:0xf bank_mask:0x3
	v_mov_b32_dpp v33, v37 row_ror:8 row_mask:0xf bank_mask:0x3
	v_mov_b32_dpp v34, v38 row_ror:8 row_mask:0xf bank_mask:0x3
	v_mov_b32_dpp v35, v39 row_ror:8 row_mask:0xf bank_mask:0x3
	v_mov_b32_dpp v36, v132 row_ror:8 row_mask:0xf bank_mask:0xc
	v_mov_b32_dpp v37, v133 row_ror:8 row_mask:0xf bank_mask:0xc
	v_mov_b32_dpp v38, v134 row_ror:8 row_mask:0xf bank_mask:0xc
	v_mov_b32_dpp v39, v135 row_ror:8 row_mask:0xf bank_mask:0xc
	v_mov_b32_e32 v132, v24
	v_mov_b32_e32 v133, v25
	v_mov_b32_e32 v134, v26
	v_mov_b32_e32 v135, v27
	v_mov_b32_dpp v24, v28 row_ror:8 row_mask:0xf bank_mask:0x3
	v_mov_b32_dpp v25, v29 row_ror:8 row_mask:0xf bank_mask:0x3
	v_mov_b32_dpp v26, v30 row_ror:8 row_mask:0xf bank_mask:0x3
	v_mov_b32_dpp v27, v31 row_ror:8 row_mask:0xf bank_mask:0x3
	v_mov_b32_dpp v28, v132 row_ror:8 row_mask:0xf bank_mask:0xc
	v_mov_b32_dpp v29, v133 row_ror:8 row_mask:0xf bank_mask:0xc
	v_mov_b32_dpp v30, v134 row_ror:8 row_mask:0xf bank_mask:0xc
	v_mov_b32_dpp v31, v135 row_ror:8 row_mask:0xf bank_mask:0xc
	v_mov_b32_e32 v132, v16
	v_mov_b32_e32 v133, v17
	v_mov_b32_e32 v134, v18
	v_mov_b32_e32 v135, v19
	v_mov_b32_dpp v16, v20 row_ror:8 row_mask:0xf bank_mask:0x3
	v_mov_b32_dpp v17, v21 row_ror:8 row_mask:0xf bank_mask:0x3
	v_mov_b32_dpp v18, v22 row_ror:8 row_mask:0xf bank_mask:0x3
	v_mov_b32_dpp v19, v23 row_ror:8 row_mask:0xf bank_mask:0x3
	v_mov_b32_dpp v20, v132 row_ror:8 row_mask:0xf bank_mask:0xc
	v_mov_b32_dpp v21, v133 row_ror:8 row_mask:0xf bank_mask:0xc
	v_mov_b32_dpp v22, v134 row_ror:8 row_mask:0xf bank_mask:0xc
	v_mov_b32_dpp v23, v135 row_ror:8 row_mask:0xf bank_mask:0xc
	v_mov_b32_e32 v132, v8
	v_mov_b32_e32 v133, v9
	v_mov_b32_e32 v134, v10
	v_mov_b32_e32 v135, v11
	v_mov_b32_dpp v8, v12 row_ror:8 row_mask:0xf bank_mask:0x3
	v_mov_b32_dpp v9, v13 row_ror:8 row_mask:0xf bank_mask:0x3
	v_mov_b32_dpp v10, v14 row_ror:8 row_mask:0xf bank_mask:0x3
	v_mov_b32_dpp v11, v15 row_ror:8 row_mask:0xf bank_mask:0x3
	v_mov_b32_dpp v12, v132 row_ror:8 row_mask:0xf bank_mask:0xc
	v_mov_b32_dpp v13, v133 row_ror:8 row_mask:0xf bank_mask:0xc
	v_mov_b32_dpp v14, v134 row_ror:8 row_mask:0xf bank_mask:0xc
	v_mov_b32_dpp v15, v135 row_ror:8 row_mask:0xf bank_mask:0xc
	v_mov_b32_e32 v132, v0
	v_mov_b32_e32 v133, v1
	v_mov_b32_e32 v134, v2
	v_mov_b32_e32 v135, v3
	v_mov_b32_dpp v0, v4 row_ror:8 row_mask:0xf bank_mask:0x3
	v_mov_b32_dpp v1, v5 row_ror:8 row_mask:0xf bank_mask:0x3
	v_mov_b32_dpp v2, v6 row_ror:8 row_mask:0xf bank_mask:0x3
	v_mov_b32_dpp v3, v7 row_ror:8 row_mask:0xf bank_mask:0x3
	v_mov_b32_dpp v4, v132 row_ror:8 row_mask:0xf bank_mask:0xc
	v_mov_b32_dpp v5, v133 row_ror:8 row_mask:0xf bank_mask:0xc
	v_mov_b32_dpp v6, v134 row_ror:8 row_mask:0xf bank_mask:0xc
	v_mov_b32_dpp v7, v135 row_ror:8 row_mask:0xf bank_mask:0xc
	v_add_u32_e32 v206, 0x0, v224
	v_add_u32_e32 v207, 0x10000, v224
	v_add_u32_e32 v208, 0x20000, v224
	v_add_u32_e32 v209, 0x30000, v224
	global_load_dwordx4 v[112:115], v206, s[60:61]
	global_load_dwordx4 v[116:119], v206, s[60:61] offset:512
	global_load_dwordx4 v[120:123], v207, s[60:61]
	global_load_dwordx4 v[124:127], v207, s[60:61] offset:512
	global_load_dwordx4 v[148:151], v208, s[60:61]
	global_load_dwordx4 v[152:155], v208, s[60:61] offset:512
	global_load_dwordx4 v[156:159], v209, s[60:61]
	global_load_dwordx4 v[164:167], v209, s[60:61] offset:512
	v_add_u32_e32 v210, 0x40000, v224
	v_add_u32_e32 v211, 0x50000, v224
	v_add_u32_e32 v222, 0x60000, v224
	v_add_u32_e32 v223, 0x70000, v224
	global_load_dwordx4 v[168:171], v210, s[60:61]
	global_load_dwordx4 v[172:175], v210, s[60:61] offset:512
	global_load_dwordx4 v[176:179], v211, s[60:61]
	global_load_dwordx4 v[180:183], v211, s[60:61] offset:512
	global_load_dwordx4 v[184:187], v222, s[60:61]
	global_load_dwordx4 v[194:197], v222, s[60:61] offset:512
	global_load_dwordx4 v[198:201], v223, s[60:61]
	global_load_dwordx4 v[202:205], v223, s[60:61] offset:512
	s_waitcnt vmcnt(15)
; __device__ __forceinline__ unsigned cvt_pk_bf16(float lo, float hi) { typedef float f2_t __attribute__((ext_vector_type(2))); typedef __bf16 b2_t __attribute__((ext_vector_type(2))); const f2_t v = {lo, hi}; return __builtin_bit_cast(unsigned, __builtin_convertvector(v, b2_t)); }
;     __device__ __forceinline__ void operator()(const f32x4 (&acc)[2][2][4][2], const Unit& u, int wr, int wc, int fr, int fq) const {
;     ...
;                 for (int mm = 0; mm < 2; ++mm) { const size_t off = (size_t)(row0 + (ch >> 1) * HALF + ((ch & 1) * 2 + mm) * 16) * ldc + col0;
; #pragma unroll
;                     for (int bj = 0; bj < 2; ++bj)
; #pragma unroll
;                         for (int n = 0; n < 2; ++n) b[ch & 1][mm][bj][n] = *(const f32x4*)(base + off + bj * HALF + n * 16); }
;             }
;             asm volatile("" ::: "memory");
;             if (ch > 0) {
;                 const int pc = ch - 1, ai = pc >> 1;
; #pragma unroll
;                 for (int mm = 0; mm < 2; ++mm) { const int m = (pc & 1) * 2 + mm, row = row0 + ai * HALF + m * 16; const size_t off = (size_t)row * ldc + col0;
;                     float s = 0.f;
; #pragma unroll
;                     for (int bj = 0; bj < 2; ++bj)
; #pragma unroll
;                         for (int n = 0; n < 2; ++n) {
;                             const f32x4 o = b[pc & 1][mm][bj][n] + acc[ai][bj][m][n] * scale;
;                             *(f32x4*)(out + off + bj * HALF + n * 16) = o;
;                             if (NORM) { s += (o[0] * o[0] + o[1] * o[1]) + (o[2] * o[2] + o[3] * o[3]);
;                                 u32x2 w; w.x = cvt_pk_bf16(o[0], o[1]); w.y = cvt_pk_bf16(o[2], o[3]); *(u32x2*)(xb + off + bj * HALF + n * 16) = w; }
;                         }
;                     if (NORM) { s += __shfl_xor(s, 16); s += __shfl_xor(s, 32); ssq[(size_t)row * 32 + u.pn * 4 + wc] = s; }
	v_pk_fma_f32 v[160:161], v[160:161], 0.5, v[112:113] op_sel_hi:[1,0,1]
	v_pk_fma_f32 v[162:163], v[162:163], 0.5, v[114:115] op_sel_hi:[1,0,1]
	s_waitcnt vmcnt(14)
	v_pk_fma_f32 v[136:137], v[136:137], 0.5, v[116:117] op_sel_hi:[1,0,1]
	v_pk_fma_f32 v[138:139], v[138:139], 0.5, v[118:119] op_sel_hi:[1,0,1]
	s_waitcnt vmcnt(13)
	v_pk_fma_f32 v[144:145], v[144:145], 0.5, v[120:121] op_sel_hi:[1,0,1]
	v_pk_fma_f32 v[146:147], v[146:147], 0.5, v[122:123] op_sel_hi:[1,0,1]
	s_waitcnt vmcnt(12)
	v_pk_fma_f32 v[128:129], v[128:129], 0.5, v[124:125] op_sel_hi:[1,0,1]
	v_pk_fma_f32 v[130:131], v[130:131], 0.5, v[126:127] op_sel_hi:[1,0,1]
	s_waitcnt vmcnt(11)
	v_pk_fma_f32 v[108:109], v[108:109], 0.5, v[148:149] op_sel_hi:[1,0,1]
	v_pk_fma_f32 v[110:111], v[110:111], 0.5, v[150:151] op_sel_hi:[1,0,1]
	s_waitcnt vmcnt(10)
	v_pk_fma_f32 v[100:101], v[100:101], 0.5, v[152:153] op_sel_hi:[1,0,1]
	v_pk_fma_f32 v[102:103], v[102:103], 0.5, v[154:155] op_sel_hi:[1,0,1]
	s_waitcnt vmcnt(9)
	v_pk_fma_f32 v[104:105], v[104:105], 0.5, v[156:157] op_sel_hi:[1,0,1]
	v_pk_fma_f32 v[106:107], v[106:107], 0.5, v[158:159] op_sel_hi:[1,0,1]
	s_waitcnt vmcnt(8)
	v_pk_fma_f32 v[96:97], v[96:97], 0.5, v[164:165] op_sel_hi:[1,0,1]
	v_pk_fma_f32 v[98:99], v[98:99], 0.5, v[166:167] op_sel_hi:[1,0,1]
	global_store_dwordx4 v206, v[160:163], s[88:89]
	global_store_dwordx4 v206, v[136:139], s[88:89] offset:512
	global_store_dwordx4 v207, v[144:147], s[88:89]
	global_store_dwordx4 v207, v[128:131], s[88:89] offset:512
	global_store_dwordx4 v208, v[108:111], s[88:89]
	global_store_dwordx4 v208, v[100:103], s[88:89] offset:512
	global_store_dwordx4 v209, v[104:107], s[88:89]
	global_store_dwordx4 v209, v[96:99], s[88:89] offset:512
	v_mul_f32_e32 v235, v160, v160
	v_fmac_f32_e32 v235, v161, v161
	v_fmac_f32_e32 v235, v162, v162
	v_fmac_f32_e32 v235, v163, v163
	v_fmac_f32_e32 v235, v136, v136
	v_fmac_f32_e32 v235, v137, v137
	v_fmac_f32_e32 v235, v138, v138
	v_fmac_f32_e32 v235, v139, v139
	v_mul_f32_e32 v236, v144, v144
	v_fmac_f32_e32 v236, v145, v145
	v_fmac_f32_e32 v236, v146, v146
	v_fmac_f32_e32 v236, v147, v147
	v_fmac_f32_e32 v236, v128, v128
	v_fmac_f32_e32 v236, v129, v129
	v_fmac_f32_e32 v236, v130, v130
	v_fmac_f32_e32 v236, v131, v131
	v_mul_f32_e32 v237, v108, v108
	v_fmac_f32_e32 v237, v109, v109
	v_fmac_f32_e32 v237, v110, v110
	v_fmac_f32_e32 v237, v111, v111
	v_fmac_f32_e32 v237, v100, v100
	v_fmac_f32_e32 v237, v101, v101
	v_fmac_f32_e32 v237, v102, v102
	v_fmac_f32_e32 v237, v103, v103
	v_mul_f32_e32 v238, v104, v104
	v_fmac_f32_e32 v238, v105, v105
	v_fmac_f32_e32 v238, v106, v106
	v_fmac_f32_e32 v238, v107, v107
	v_fmac_f32_e32 v238, v96, v96
	v_fmac_f32_e32 v238, v97, v97
	v_fmac_f32_e32 v238, v98, v98
	v_fmac_f32_e32 v238, v99, v99
	v_cvt_pk_bf16_f32 v112, v160, v161
	v_cvt_pk_bf16_f32 v113, v162, v163
	v_cvt_pk_bf16_f32 v116, v136, v137
	v_cvt_pk_bf16_f32 v117, v138, v139
	v_cvt_pk_bf16_f32 v120, v144, v145
	v_cvt_pk_bf16_f32 v121, v146, v147
	v_cvt_pk_bf16_f32 v124, v128, v129
	v_cvt_pk_bf16_f32 v125, v130, v131
	v_cvt_pk_bf16_f32 v148, v108, v109
	v_cvt_pk_bf16_f32 v149, v110, v111
	v_cvt_pk_bf16_f32 v152, v100, v101
	v_cvt_pk_bf16_f32 v153, v102, v103
	v_cvt_pk_bf16_f32 v156, v104, v105
	v_cvt_pk_bf16_f32 v157, v106, v107
	v_cvt_pk_bf16_f32 v164, v96, v97
	v_cvt_pk_bf16_f32 v165, v98, v99
	v_add_u32_e32 v239, 0x0, v234
	v_add_u32_e32 v240, 0x8000, v234
	v_add_u32_e32 v241, 0x10000, v234
	v_add_u32_e32 v242, 0x18000, v234
	global_store_dwordx2 v239, v[112:113], s[36:37]
	global_store_dwordx2 v239, v[116:117], s[36:37] offset:256
	global_store_dwordx2 v240, v[120:121], s[36:37]
	global_store_dwordx2 v240, v[124:125], s[36:37] offset:256
	global_store_dwordx2 v241, v[148:149], s[36:37]
	global_store_dwordx2 v241, v[152:153], s[36:37] offset:256
	global_store_dwordx2 v242, v[156:157], s[36:37]
	global_store_dwordx2 v242, v[164:165], s[36:37] offset:256
	ds_bpermute_b32 v243, v230, v235
	ds_bpermute_b32 v244, v230, v236
	ds_bpermute_b32 v245, v230, v237
	ds_bpermute_b32 v246, v230, v238
	s_waitcnt lgkmcnt(0)
	v_add_f32_e32 v235, v235, v243
	v_add_f32_e32 v236, v236, v244
	v_add_f32_e32 v237, v237, v245
	v_add_f32_e32 v238, v238, v246
	ds_bpermute_b32 v243, v231, v235
	ds_bpermute_b32 v244, v231, v236
	ds_bpermute_b32 v245, v231, v237
	ds_bpermute_b32 v246, v231, v238
	s_waitcnt lgkmcnt(0)
	v_add_f32_e32 v235, v235, v243
	v_add_f32_e32 v236, v236, v244
	v_add_f32_e32 v237, v237, v245
	v_add_f32_e32 v238, v238, v246
	s_nop 1
	v_add_f32_dpp v243, v235, v235 row_ror:8 row_mask:0xf bank_mask:0xf
	v_add_f32_dpp v244, v236, v236 row_ror:8 row_mask:0xf bank_mask:0xf
	v_add_f32_dpp v245, v237, v237 row_ror:8 row_mask:0xf bank_mask:0xf
	v_add_f32_dpp v246, v238, v238 row_ror:8 row_mask:0xf bank_mask:0xf
	v_cndmask_b32_e64 v247, v243, v244, s[62:63]
	v_add_u32_e32 v249, 0x0, v232
	v_cndmask_b32_e64 v248, v245, v246, s[62:63]
	v_add_u32_e32 v250, 0x800, v232
	global_store_dword v249, v247, s[48:49]
	global_store_dword v250, v248, s[48:49]
	v_add_u32_e32 v206, 0x100000, v224
	v_add_u32_e32 v207, 0x110000, v224
	v_add_u32_e32 v208, 0x120000, v224
	v_add_u32_e32 v209, 0x130000, v224
	global_load_dwordx4 v[112:115], v206, s[60:61]
	global_load_dwordx4 v[116:119], v206, s[60:61] offset:512
	global_load_dwordx4 v[120:123], v207, s[60:61]
	global_load_dwordx4 v[124:127], v207, s[60:61] offset:512
	global_load_dwordx4 v[148:151], v208, s[60:61]
	global_load_dwordx4 v[152:155], v208, s[60:61] offset:512
	global_load_dwordx4 v[156:159], v209, s[60:61]
	global_load_dwordx4 v[164:167], v209, s[60:61] offset:512
	s_waitcnt vmcnt(33)
; __device__ __forceinline__ unsigned cvt_pk_bf16(float lo, float hi) { typedef float f2_t __attribute__((ext_vector_type(2))); typedef __bf16 b2_t __attribute__((ext_vector_type(2))); const f2_t v = {lo, hi}; return __builtin_bit_cast(unsigned, __builtin_convertvector(v, b2_t)); }
;     __device__ __forceinline__ void operator()(const f32x4 (&acc)[2][2][4][2], const Unit& u, int wr, int wc, int fr, int fq) const {
;     ...
;                 for (int mm = 0; mm < 2; ++mm) { const size_t off = (size_t)(row0 + (ch >> 1) * HALF + ((ch & 1) * 2 + mm) * 16) * ldc + col0;
; #pragma unroll
;                     for (int bj = 0; bj < 2; ++bj)
; #pragma unroll
;                         for (int n = 0; n < 2; ++n) b[ch & 1][mm][bj][n] = *(const f32x4*)(base + off + bj * HALF + n * 16); }
;             }
;             asm volatile("" ::: "memory");
;             if (ch > 0) {
;                 const int pc = ch - 1, ai = pc >> 1;
; #pragma unroll
;                 for (int mm = 0; mm < 2; ++mm) { const int m = (pc & 1) * 2 + mm, row = row0 + ai * HALF + m * 16; const size_t off = (size_t)row * ldc + col0;
;                     float s = 0.f;
; #pragma unroll
;                     for (int bj = 0; bj < 2; ++bj)
; #pragma unroll
;                         for (int n = 0; n < 2; ++n) {
;                             const f32x4 o = b[pc & 1][mm][bj][n] + acc[ai][bj][m][n] * scale;
;                             *(f32x4*)(out + off + bj * HALF + n * 16) = o;
;                             if (NORM) { s += (o[0] * o[0] + o[1] * o[1]) + (o[2] * o[2] + o[3] * o[3]);
;                                 u32x2 w; w.x = cvt_pk_bf16(o[0], o[1]); w.y = cvt_pk_bf16(o[2], o[3]); *(u32x2*)(xb + off + bj * HALF + n * 16) = w; }
;                         }
;                     if (NORM) { s += __shfl_xor(s, 16); s += __shfl_xor(s, 32); ssq[(size_t)row * 32 + u.pn * 4 + wc] = s; }
	v_pk_fma_f32 v[92:93], v[92:93], 0.5, v[168:169] op_sel_hi:[1,0,1]
	v_pk_fma_f32 v[94:95], v[94:95], 0.5, v[170:171] op_sel_hi:[1,0,1]
	s_waitcnt vmcnt(32)
	v_pk_fma_f32 v[84:85], v[84:85], 0.5, v[172:173] op_sel_hi:[1,0,1]
	v_pk_fma_f32 v[86:87], v[86:87], 0.5, v[174:175] op_sel_hi:[1,0,1]
	s_waitcnt vmcnt(31)
	v_pk_fma_f32 v[88:89], v[88:89], 0.5, v[176:177] op_sel_hi:[1,0,1]
	v_pk_fma_f32 v[90:91], v[90:91], 0.5, v[178:179] op_sel_hi:[1,0,1]
	s_waitcnt vmcnt(30)
	v_pk_fma_f32 v[80:81], v[80:81], 0.5, v[180:181] op_sel_hi:[1,0,1]
	v_pk_fma_f32 v[82:83], v[82:83], 0.5, v[182:183] op_sel_hi:[1,0,1]
	s_waitcnt vmcnt(29)
	v_pk_fma_f32 v[76:77], v[76:77], 0.5, v[184:185] op_sel_hi:[1,0,1]
	v_pk_fma_f32 v[78:79], v[78:79], 0.5, v[186:187] op_sel_hi:[1,0,1]
	s_waitcnt vmcnt(28)
	v_pk_fma_f32 v[68:69], v[68:69], 0.5, v[194:195] op_sel_hi:[1,0,1]
	v_pk_fma_f32 v[70:71], v[70:71], 0.5, v[196:197] op_sel_hi:[1,0,1]
	s_waitcnt vmcnt(27)
	v_pk_fma_f32 v[72:73], v[72:73], 0.5, v[198:199] op_sel_hi:[1,0,1]
	v_pk_fma_f32 v[74:75], v[74:75], 0.5, v[200:201] op_sel_hi:[1,0,1]
	s_waitcnt vmcnt(26)
	v_pk_fma_f32 v[64:65], v[64:65], 0.5, v[202:203] op_sel_hi:[1,0,1]
	v_pk_fma_f32 v[66:67], v[66:67], 0.5, v[204:205] op_sel_hi:[1,0,1]
	global_store_dwordx4 v210, v[92:95], s[88:89]
	global_store_dwordx4 v210, v[84:87], s[88:89] offset:512
	global_store_dwordx4 v211, v[88:91], s[88:89]
	global_store_dwordx4 v211, v[80:83], s[88:89] offset:512
	global_store_dwordx4 v222, v[76:79], s[88:89]
	global_store_dwordx4 v222, v[68:71], s[88:89] offset:512
	global_store_dwordx4 v223, v[72:75], s[88:89]
	global_store_dwordx4 v223, v[64:67], s[88:89] offset:512
	v_mul_f32_e32 v235, v92, v92
	v_fmac_f32_e32 v235, v93, v93
	v_fmac_f32_e32 v235, v94, v94
	v_fmac_f32_e32 v235, v95, v95
	v_fmac_f32_e32 v235, v84, v84
	v_fmac_f32_e32 v235, v85, v85
	v_fmac_f32_e32 v235, v86, v86
	v_fmac_f32_e32 v235, v87, v87
	v_mul_f32_e32 v236, v88, v88
	v_fmac_f32_e32 v236, v89, v89
	v_fmac_f32_e32 v236, v90, v90
	v_fmac_f32_e32 v236, v91, v91
	v_fmac_f32_e32 v236, v80, v80
	v_fmac_f32_e32 v236, v81, v81
	v_fmac_f32_e32 v236, v82, v82
	v_fmac_f32_e32 v236, v83, v83
	v_mul_f32_e32 v237, v76, v76
	v_fmac_f32_e32 v237, v77, v77
	v_fmac_f32_e32 v237, v78, v78
	v_fmac_f32_e32 v237, v79, v79
	v_fmac_f32_e32 v237, v68, v68
	v_fmac_f32_e32 v237, v69, v69
	v_fmac_f32_e32 v237, v70, v70
	v_fmac_f32_e32 v237, v71, v71
	v_mul_f32_e32 v238, v72, v72
	v_fmac_f32_e32 v238, v73, v73
	v_fmac_f32_e32 v238, v74, v74
	v_fmac_f32_e32 v238, v75, v75
	v_fmac_f32_e32 v238, v64, v64
	v_fmac_f32_e32 v238, v65, v65
	v_fmac_f32_e32 v238, v66, v66
	v_fmac_f32_e32 v238, v67, v67
	v_cvt_pk_bf16_f32 v168, v92, v93
	v_cvt_pk_bf16_f32 v169, v94, v95
	v_cvt_pk_bf16_f32 v172, v84, v85
	v_cvt_pk_bf16_f32 v173, v86, v87
	v_cvt_pk_bf16_f32 v176, v88, v89
	v_cvt_pk_bf16_f32 v177, v90, v91
	v_cvt_pk_bf16_f32 v180, v80, v81
	v_cvt_pk_bf16_f32 v181, v82, v83
	v_cvt_pk_bf16_f32 v184, v76, v77
	v_cvt_pk_bf16_f32 v185, v78, v79
	v_cvt_pk_bf16_f32 v194, v68, v69
	v_cvt_pk_bf16_f32 v195, v70, v71
	v_cvt_pk_bf16_f32 v198, v72, v73
	v_cvt_pk_bf16_f32 v199, v74, v75
	v_cvt_pk_bf16_f32 v202, v64, v65
	v_cvt_pk_bf16_f32 v203, v66, v67
	v_add_u32_e32 v239, 0x20000, v234
	v_add_u32_e32 v240, 0x28000, v234
	v_add_u32_e32 v241, 0x30000, v234
	v_add_u32_e32 v242, 0x38000, v234
	global_store_dwordx2 v239, v[168:169], s[36:37]
	global_store_dwordx2 v239, v[172:173], s[36:37] offset:256
	global_store_dwordx2 v240, v[176:177], s[36:37]
	global_store_dwordx2 v240, v[180:181], s[36:37] offset:256
	global_store_dwordx2 v241, v[184:185], s[36:37]
	global_store_dwordx2 v241, v[194:195], s[36:37] offset:256
	global_store_dwordx2 v242, v[198:199], s[36:37]
	global_store_dwordx2 v242, v[202:203], s[36:37] offset:256
	ds_bpermute_b32 v243, v230, v235
	ds_bpermute_b32 v244, v230, v236
	ds_bpermute_b32 v245, v230, v237
	ds_bpermute_b32 v246, v230, v238
	s_waitcnt lgkmcnt(0)
	v_add_f32_e32 v235, v235, v243
	v_add_f32_e32 v236, v236, v244
	v_add_f32_e32 v237, v237, v245
	v_add_f32_e32 v238, v238, v246
	ds_bpermute_b32 v243, v231, v235
	ds_bpermute_b32 v244, v231, v236
	ds_bpermute_b32 v245, v231, v237
	ds_bpermute_b32 v246, v231, v238
	s_waitcnt lgkmcnt(0)
	v_add_f32_e32 v235, v235, v243
	v_add_f32_e32 v236, v236, v244
	v_add_f32_e32 v237, v237, v245
	v_add_f32_e32 v238, v238, v246
	s_nop 1
	v_add_f32_dpp v243, v235, v235 row_ror:8 row_mask:0xf bank_mask:0xf
	v_add_f32_dpp v244, v236, v236 row_ror:8 row_mask:0xf bank_mask:0xf
	v_add_f32_dpp v245, v237, v237 row_ror:8 row_mask:0xf bank_mask:0xf
	v_add_f32_dpp v246, v238, v238 row_ror:8 row_mask:0xf bank_mask:0xf
	v_cndmask_b32_e64 v247, v243, v244, s[62:63]
	v_add_u32_e32 v249, 0x1000, v232
	v_cndmask_b32_e64 v248, v245, v246, s[62:63]
	v_add_u32_e32 v250, 0x1800, v232
	global_store_dword v249, v247, s[48:49]
	global_store_dword v250, v248, s[48:49]
	v_add_u32_e32 v210, 0x140000, v224
	v_add_u32_e32 v211, 0x150000, v224
	v_add_u32_e32 v222, 0x160000, v224
	v_add_u32_e32 v223, 0x170000, v224
	global_load_dwordx4 v[168:171], v210, s[60:61]
	global_load_dwordx4 v[172:175], v210, s[60:61] offset:512
	global_load_dwordx4 v[176:179], v211, s[60:61]
	global_load_dwordx4 v[180:183], v211, s[60:61] offset:512
	global_load_dwordx4 v[184:187], v222, s[60:61]
	global_load_dwordx4 v[194:197], v222, s[60:61] offset:512
	global_load_dwordx4 v[198:201], v223, s[60:61]
	global_load_dwordx4 v[202:205], v223, s[60:61] offset:512
	s_waitcnt vmcnt(33)
	v_pk_fma_f32 v[60:61], v[60:61], 0.5, v[112:113] op_sel_hi:[1,0,1]
	v_pk_fma_f32 v[62:63], v[62:63], 0.5, v[114:115] op_sel_hi:[1,0,1]
	s_waitcnt vmcnt(32)
; __device__ __forceinline__ unsigned cvt_pk_bf16(float lo, float hi) { typedef float f2_t __attribute__((ext_vector_type(2))); typedef __bf16 b2_t __attribute__((ext_vector_type(2))); const f2_t v = {lo, hi}; return __builtin_bit_cast(unsigned, __builtin_convertvector(v, b2_t)); }
;     __device__ __forceinline__ void operator()(const f32x4 (&acc)[2][2][4][2], const Unit& u, int wr, int wc, int fr, int fq) const {
;     ...
;                 for (int mm = 0; mm < 2; ++mm) { const size_t off = (size_t)(row0 + (ch >> 1) * HALF + ((ch & 1) * 2 + mm) * 16) * ldc + col0;
; #pragma unroll
;                     for (int bj = 0; bj < 2; ++bj)
; #pragma unroll
;                         for (int n = 0; n < 2; ++n) b[ch & 1][mm][bj][n] = *(const f32x4*)(base + off + bj * HALF + n * 16); }
;             }
;             asm volatile("" ::: "memory");
;             if (ch > 0) {
;                 const int pc = ch - 1, ai = pc >> 1;
; #pragma unroll
;                 for (int mm = 0; mm < 2; ++mm) { const int m = (pc & 1) * 2 + mm, row = row0 + ai * HALF + m * 16; const size_t off = (size_t)row * ldc + col0;
;                     float s = 0.f;
; #pragma unroll
;                     for (int bj = 0; bj < 2; ++bj)
; #pragma unroll
;                         for (int n = 0; n < 2; ++n) {
;                             const f32x4 o = b[pc & 1][mm][bj][n] + acc[ai][bj][m][n] * scale;
;                             *(f32x4*)(out + off + bj * HALF + n * 16) = o;
;                             if (NORM) { s += (o[0] * o[0] + o[1] * o[1]) + (o[2] * o[2] + o[3] * o[3]);
;                                 u32x2 w; w.x = cvt_pk_bf16(o[0], o[1]); w.y = cvt_pk_bf16(o[2], o[3]); *(u32x2*)(xb + off + bj * HALF + n * 16) = w; }
;                         }
;                     if (NORM) { s += __shfl_xor(s, 16); s += __shfl_xor(s, 32); ssq[(size_t)row * 32 + u.pn * 4 + wc] = s; }
	v_pk_fma_f32 v[52:53], v[52:53], 0.5, v[116:117] op_sel_hi:[1,0,1]
	v_pk_fma_f32 v[54:55], v[54:55], 0.5, v[118:119] op_sel_hi:[1,0,1]
	s_waitcnt vmcnt(31)
	v_pk_fma_f32 v[56:57], v[56:57], 0.5, v[120:121] op_sel_hi:[1,0,1]
	v_pk_fma_f32 v[58:59], v[58:59], 0.5, v[122:123] op_sel_hi:[1,0,1]
	s_waitcnt vmcnt(30)
	v_pk_fma_f32 v[48:49], v[48:49], 0.5, v[124:125] op_sel_hi:[1,0,1]
	v_pk_fma_f32 v[50:51], v[50:51], 0.5, v[126:127] op_sel_hi:[1,0,1]
	s_waitcnt vmcnt(29)
	v_pk_fma_f32 v[44:45], v[44:45], 0.5, v[148:149] op_sel_hi:[1,0,1]
	v_pk_fma_f32 v[46:47], v[46:47], 0.5, v[150:151] op_sel_hi:[1,0,1]
	s_waitcnt vmcnt(28)
	v_pk_fma_f32 v[36:37], v[36:37], 0.5, v[152:153] op_sel_hi:[1,0,1]
	v_pk_fma_f32 v[38:39], v[38:39], 0.5, v[154:155] op_sel_hi:[1,0,1]
	s_waitcnt vmcnt(27)
	v_pk_fma_f32 v[40:41], v[40:41], 0.5, v[156:157] op_sel_hi:[1,0,1]
	v_pk_fma_f32 v[42:43], v[42:43], 0.5, v[158:159] op_sel_hi:[1,0,1]
	s_waitcnt vmcnt(26)
	v_pk_fma_f32 v[32:33], v[32:33], 0.5, v[164:165] op_sel_hi:[1,0,1]
	v_pk_fma_f32 v[34:35], v[34:35], 0.5, v[166:167] op_sel_hi:[1,0,1]
	global_store_dwordx4 v206, v[60:63], s[88:89]
	global_store_dwordx4 v206, v[52:55], s[88:89] offset:512
	global_store_dwordx4 v207, v[56:59], s[88:89]
	global_store_dwordx4 v207, v[48:51], s[88:89] offset:512
	global_store_dwordx4 v208, v[44:47], s[88:89]
	global_store_dwordx4 v208, v[36:39], s[88:89] offset:512
	global_store_dwordx4 v209, v[40:43], s[88:89]
	global_store_dwordx4 v209, v[32:35], s[88:89] offset:512
	v_mul_f32_e32 v235, v60, v60
	v_fmac_f32_e32 v235, v61, v61
	v_fmac_f32_e32 v235, v62, v62
	v_fmac_f32_e32 v235, v63, v63
	v_fmac_f32_e32 v235, v52, v52
	v_fmac_f32_e32 v235, v53, v53
	v_fmac_f32_e32 v235, v54, v54
	v_fmac_f32_e32 v235, v55, v55
	v_mul_f32_e32 v236, v56, v56
	v_fmac_f32_e32 v236, v57, v57
	v_fmac_f32_e32 v236, v58, v58
	v_fmac_f32_e32 v236, v59, v59
	v_fmac_f32_e32 v236, v48, v48
	v_fmac_f32_e32 v236, v49, v49
	v_fmac_f32_e32 v236, v50, v50
	v_fmac_f32_e32 v236, v51, v51
	v_mul_f32_e32 v237, v44, v44
	v_fmac_f32_e32 v237, v45, v45
	v_fmac_f32_e32 v237, v46, v46
	v_fmac_f32_e32 v237, v47, v47
	v_fmac_f32_e32 v237, v36, v36
	v_fmac_f32_e32 v237, v37, v37
	v_fmac_f32_e32 v237, v38, v38
	v_fmac_f32_e32 v237, v39, v39
	v_mul_f32_e32 v238, v40, v40
	v_fmac_f32_e32 v238, v41, v41
	v_fmac_f32_e32 v238, v42, v42
	v_fmac_f32_e32 v238, v43, v43
	v_fmac_f32_e32 v238, v32, v32
	v_fmac_f32_e32 v238, v33, v33
	v_fmac_f32_e32 v238, v34, v34
	v_fmac_f32_e32 v238, v35, v35
	v_cvt_pk_bf16_f32 v112, v60, v61
	v_cvt_pk_bf16_f32 v113, v62, v63
	v_cvt_pk_bf16_f32 v116, v52, v53
	v_cvt_pk_bf16_f32 v117, v54, v55
	v_cvt_pk_bf16_f32 v120, v56, v57
	v_cvt_pk_bf16_f32 v121, v58, v59
	v_cvt_pk_bf16_f32 v124, v48, v49
	v_cvt_pk_bf16_f32 v125, v50, v51
	v_cvt_pk_bf16_f32 v148, v44, v45
	v_cvt_pk_bf16_f32 v149, v46, v47
	v_cvt_pk_bf16_f32 v152, v36, v37
	v_cvt_pk_bf16_f32 v153, v38, v39
	v_cvt_pk_bf16_f32 v156, v40, v41
	v_cvt_pk_bf16_f32 v157, v42, v43
	v_cvt_pk_bf16_f32 v164, v32, v33
	v_cvt_pk_bf16_f32 v165, v34, v35
	v_add_u32_e32 v239, 0x80000, v234
	v_add_u32_e32 v240, 0x88000, v234
	v_add_u32_e32 v241, 0x90000, v234
	v_add_u32_e32 v242, 0x98000, v234
	global_store_dwordx2 v239, v[112:113], s[36:37]
	global_store_dwordx2 v239, v[116:117], s[36:37] offset:256
	global_store_dwordx2 v240, v[120:121], s[36:37]
	global_store_dwordx2 v240, v[124:125], s[36:37] offset:256
	global_store_dwordx2 v241, v[148:149], s[36:37]
	global_store_dwordx2 v241, v[152:153], s[36:37] offset:256
	global_store_dwordx2 v242, v[156:157], s[36:37]
	global_store_dwordx2 v242, v[164:165], s[36:37] offset:256
	ds_bpermute_b32 v243, v230, v235
	ds_bpermute_b32 v244, v230, v236
	ds_bpermute_b32 v245, v230, v237
	ds_bpermute_b32 v246, v230, v238
	s_waitcnt lgkmcnt(0)
	v_add_f32_e32 v235, v235, v243
	v_add_f32_e32 v236, v236, v244
	v_add_f32_e32 v237, v237, v245
	v_add_f32_e32 v238, v238, v246
	ds_bpermute_b32 v243, v231, v235
	ds_bpermute_b32 v244, v231, v236
	ds_bpermute_b32 v245, v231, v237
	ds_bpermute_b32 v246, v231, v238
	s_waitcnt lgkmcnt(0)
	v_add_f32_e32 v235, v235, v243
	v_add_f32_e32 v236, v236, v244
	v_add_f32_e32 v237, v237, v245
	v_add_f32_e32 v238, v238, v246
	s_nop 1
	v_add_f32_dpp v243, v235, v235 row_ror:8 row_mask:0xf bank_mask:0xf
	v_add_f32_dpp v244, v236, v236 row_ror:8 row_mask:0xf bank_mask:0xf
	v_add_f32_dpp v245, v237, v237 row_ror:8 row_mask:0xf bank_mask:0xf
	v_add_f32_dpp v246, v238, v238 row_ror:8 row_mask:0xf bank_mask:0xf
	v_cndmask_b32_e64 v247, v243, v244, s[62:63]
	v_add_u32_e32 v249, 0x4000, v232
	v_cndmask_b32_e64 v248, v245, v246, s[62:63]
	v_add_u32_e32 v250, 0x4800, v232
	global_store_dword v249, v247, s[48:49]
	global_store_dword v250, v248, s[48:49]
	s_waitcnt vmcnt(25)
	v_pk_fma_f32 v[28:29], v[28:29], 0.5, v[168:169] op_sel_hi:[1,0,1]
	v_pk_fma_f32 v[30:31], v[30:31], 0.5, v[170:171] op_sel_hi:[1,0,1]
	s_waitcnt vmcnt(24)
	v_pk_fma_f32 v[20:21], v[20:21], 0.5, v[172:173] op_sel_hi:[1,0,1]
	v_pk_fma_f32 v[22:23], v[22:23], 0.5, v[174:175] op_sel_hi:[1,0,1]
	s_waitcnt vmcnt(23)
; __device__ __forceinline__ unsigned cvt_pk_bf16(float lo, float hi) { typedef float f2_t __attribute__((ext_vector_type(2))); typedef __bf16 b2_t __attribute__((ext_vector_type(2))); const f2_t v = {lo, hi}; return __builtin_bit_cast(unsigned, __builtin_convertvector(v, b2_t)); }
; #define PG8_BAR __builtin_amdgcn_s_barrier()
; template <class Epi, class Sched, bool ALIGN_EPI = false, bool SP2 = false>
; __device__ __forceinline__ void gemm_phase(PG8_LAS unsigned char* lds, const Gemm g, const Sched& S, const Epi& E) {
;     ...
;         if constexpr (!Epi::AFTER_DRAIN) { E(acc, cur, wr, wc, fr, fq); S.done(cur); }
;         if (!has_next) break;
;         cur = nxt; cA = nA; cB = nB; ++ui;
;         if constexpr (ALIGN_EPI) { if (wr == 1) PG8_BAR; }
;     __device__ __forceinline__ void operator()(const f32x4 (&acc)[2][2][4][2], const Unit& u, int wr, int wc, int fr, int fq) const {
;     ...
;                 for (int mm = 0; mm < 2; ++mm) { const size_t off = (size_t)(row0 + (ch >> 1) * HALF + ((ch & 1) * 2 + mm) * 16) * ldc + col0;
; #pragma unroll
;                     for (int bj = 0; bj < 2; ++bj)
; #pragma unroll
;                         for (int n = 0; n < 2; ++n) b[ch & 1][mm][bj][n] = *(const f32x4*)(base + off + bj * HALF + n * 16); }
;             }
;             asm volatile("" ::: "memory");
;             if (ch > 0) {
;                 const int pc = ch - 1, ai = pc >> 1;
; #pragma unroll
;                 for (int mm = 0; mm < 2; ++mm) { const int m = (pc & 1) * 2 + mm, row = row0 + ai * HALF + m * 16; const size_t off = (size_t)row * ldc + col0;
;                     float s = 0.f;
; #pragma unroll
;                     for (int bj = 0; bj < 2; ++bj)
; #pragma unroll
;                         for (int n = 0; n < 2; ++n) {
;                             const f32x4 o = b[pc & 1][mm][bj][n] + acc[ai][bj][m][n] * scale;
;                             *(f32x4*)(out + off + bj * HALF + n * 16) = o;
;                             if (NORM) { s += (o[0] * o[0] + o[1] * o[1]) + (o[2] * o[2] + o[3] * o[3]);
;                                 u32x2 w; w.x = cvt_pk_bf16(o[0], o[1]); w.y = cvt_pk_bf16(o[2], o[3]); *(u32x2*)(xb + off + bj * HALF + n * 16) = w; }
;                         }
;                     if (NORM) { s += __shfl_xor(s, 16); s += __shfl_xor(s, 32); ssq[(size_t)row * 32 + u.pn * 4 + wc] = s; }
	v_pk_fma_f32 v[24:25], v[24:25], 0.5, v[176:177] op_sel_hi:[1,0,1]
	v_pk_fma_f32 v[26:27], v[26:27], 0.5, v[178:179] op_sel_hi:[1,0,1]
	s_waitcnt vmcnt(22)
	v_pk_fma_f32 v[16:17], v[16:17], 0.5, v[180:181] op_sel_hi:[1,0,1]
	v_pk_fma_f32 v[18:19], v[18:19], 0.5, v[182:183] op_sel_hi:[1,0,1]
	s_waitcnt vmcnt(21)
	v_pk_fma_f32 v[12:13], v[12:13], 0.5, v[184:185] op_sel_hi:[1,0,1]
	v_pk_fma_f32 v[14:15], v[14:15], 0.5, v[186:187] op_sel_hi:[1,0,1]
	s_waitcnt vmcnt(20)
	v_pk_fma_f32 v[4:5], v[4:5], 0.5, v[194:195] op_sel_hi:[1,0,1]
	v_pk_fma_f32 v[6:7], v[6:7], 0.5, v[196:197] op_sel_hi:[1,0,1]
	s_waitcnt vmcnt(19)
	v_pk_fma_f32 v[8:9], v[8:9], 0.5, v[198:199] op_sel_hi:[1,0,1]
	v_pk_fma_f32 v[10:11], v[10:11], 0.5, v[200:201] op_sel_hi:[1,0,1]
	s_waitcnt vmcnt(18)
	v_pk_fma_f32 v[0:1], v[0:1], 0.5, v[202:203] op_sel_hi:[1,0,1]
	v_pk_fma_f32 v[2:3], v[2:3], 0.5, v[204:205] op_sel_hi:[1,0,1]
	global_store_dwordx4 v210, v[28:31], s[88:89]
	global_store_dwordx4 v210, v[20:23], s[88:89] offset:512
	global_store_dwordx4 v211, v[24:27], s[88:89]
	global_store_dwordx4 v211, v[16:19], s[88:89] offset:512
	global_store_dwordx4 v222, v[12:15], s[88:89]
	global_store_dwordx4 v222, v[4:7], s[88:89] offset:512
	global_store_dwordx4 v223, v[8:11], s[88:89]
	global_store_dwordx4 v223, v[0:3], s[88:89] offset:512
	v_mul_f32_e32 v235, v28, v28
	v_fmac_f32_e32 v235, v29, v29
	v_fmac_f32_e32 v235, v30, v30
	v_fmac_f32_e32 v235, v31, v31
	v_fmac_f32_e32 v235, v20, v20
	v_fmac_f32_e32 v235, v21, v21
	v_fmac_f32_e32 v235, v22, v22
	v_fmac_f32_e32 v235, v23, v23
	v_mul_f32_e32 v236, v24, v24
	v_fmac_f32_e32 v236, v25, v25
	v_fmac_f32_e32 v236, v26, v26
	v_fmac_f32_e32 v236, v27, v27
	v_fmac_f32_e32 v236, v16, v16
	v_fmac_f32_e32 v236, v17, v17
	v_fmac_f32_e32 v236, v18, v18
	v_fmac_f32_e32 v236, v19, v19
	v_mul_f32_e32 v237, v12, v12
	v_fmac_f32_e32 v237, v13, v13
	v_fmac_f32_e32 v237, v14, v14
	v_fmac_f32_e32 v237, v15, v15
	v_fmac_f32_e32 v237, v4, v4
	v_fmac_f32_e32 v237, v5, v5
	v_fmac_f32_e32 v237, v6, v6
	v_fmac_f32_e32 v237, v7, v7
	v_mul_f32_e32 v238, v8, v8
	v_fmac_f32_e32 v238, v9, v9
	v_fmac_f32_e32 v238, v10, v10
	v_fmac_f32_e32 v238, v11, v11
	v_fmac_f32_e32 v238, v0, v0
	v_fmac_f32_e32 v238, v1, v1
	v_fmac_f32_e32 v238, v2, v2
	v_fmac_f32_e32 v238, v3, v3
	v_cvt_pk_bf16_f32 v168, v28, v29
	v_cvt_pk_bf16_f32 v169, v30, v31
	v_cvt_pk_bf16_f32 v172, v20, v21
	v_cvt_pk_bf16_f32 v173, v22, v23
	v_cvt_pk_bf16_f32 v176, v24, v25
	v_cvt_pk_bf16_f32 v177, v26, v27
	v_cvt_pk_bf16_f32 v180, v16, v17
	v_cvt_pk_bf16_f32 v181, v18, v19
	v_cvt_pk_bf16_f32 v184, v12, v13
	v_cvt_pk_bf16_f32 v185, v14, v15
	v_cvt_pk_bf16_f32 v194, v4, v5
	v_cvt_pk_bf16_f32 v195, v6, v7
	v_cvt_pk_bf16_f32 v198, v8, v9
	v_cvt_pk_bf16_f32 v199, v10, v11
	v_cvt_pk_bf16_f32 v202, v0, v1
	v_cvt_pk_bf16_f32 v203, v2, v3
	v_add_u32_e32 v239, 0xa0000, v234
	v_add_u32_e32 v240, 0xa8000, v234
	v_add_u32_e32 v241, 0xb0000, v234
	v_add_u32_e32 v242, 0xb8000, v234
	global_store_dwordx2 v239, v[168:169], s[36:37]
	global_store_dwordx2 v239, v[172:173], s[36:37] offset:256
	global_store_dwordx2 v240, v[176:177], s[36:37]
	global_store_dwordx2 v240, v[180:181], s[36:37] offset:256
	global_store_dwordx2 v241, v[184:185], s[36:37]
	global_store_dwordx2 v241, v[194:195], s[36:37] offset:256
	global_store_dwordx2 v242, v[198:199], s[36:37]
	global_store_dwordx2 v242, v[202:203], s[36:37] offset:256
	ds_bpermute_b32 v243, v230, v235
	ds_bpermute_b32 v244, v230, v236
	ds_bpermute_b32 v245, v230, v237
	ds_bpermute_b32 v246, v230, v238
	s_waitcnt lgkmcnt(0)
	v_add_f32_e32 v235, v235, v243
	v_add_f32_e32 v236, v236, v244
	v_add_f32_e32 v237, v237, v245
	v_add_f32_e32 v238, v238, v246
	ds_bpermute_b32 v243, v231, v235
	ds_bpermute_b32 v244, v231, v236
	ds_bpermute_b32 v245, v231, v237
	ds_bpermute_b32 v246, v231, v238
	s_waitcnt lgkmcnt(0)
	v_add_f32_e32 v235, v235, v243
	v_add_f32_e32 v236, v236, v244
	v_add_f32_e32 v237, v237, v245
	v_add_f32_e32 v238, v238, v246
	s_nop 1
	v_add_f32_dpp v243, v235, v235 row_ror:8 row_mask:0xf bank_mask:0xf
	v_add_f32_dpp v244, v236, v236 row_ror:8 row_mask:0xf bank_mask:0xf
	v_add_f32_dpp v245, v237, v237 row_ror:8 row_mask:0xf bank_mask:0xf
	v_add_f32_dpp v246, v238, v238 row_ror:8 row_mask:0xf bank_mask:0xf
	v_cndmask_b32_e64 v247, v243, v244, s[62:63]
	v_add_u32_e32 v249, 0x5000, v232
	v_cndmask_b32_e64 v248, v245, v246, s[62:63]
	v_add_u32_e32 v250, 0x5800, v232
	global_store_dword v249, v247, s[48:49]
	global_store_dword v250, v248, s[48:49]
	v_readlane_b32 s50, v254, 9
	v_readlane_b32 s51, v254, 10
	v_readlane_b32 s52, v254, 11
	v_readlane_b32 s53, v254, 12
	v_readlane_b32 s54, v254, 13
	v_readlane_b32 s55, v254, 14
	v_readlane_b32 s56, v254, 15
	v_readlane_b32 s57, v254, 16
	v_readlane_b32 s58, v254, 17
	v_readlane_b32 s59, v254, 18
	v_readlane_b32 s60, v254, 19
	v_readlane_b32 s61, v254, 20
	v_readlane_b32 s62, v254, 21
	v_readlane_b32 s63, v254, 22
	s_mov_b64 s[46:47], -1
	s_cbranch_vccnz .LBB0_183
	s_andn2_b64 vcc, exec, s[26:27]
	s_cbranch_vccnz .LBB0_182
	s_barrier
	s_branch .LBB0_182

;     __device__ __forceinline__ void operator()(const f32x4 (&acc)[2][2][4][2], const Unit& u, int wr, int wc, int fr, int fq) const {
;         int row0 = u.pm * BM + wr * 64 + fr, col0 = u.pn * BM + wc * 32 + 4 * fq;
;         asm volatile("" : "+v"(row0), "+v"(col0));
;     ...
;                     if (NORM) { s += __shfl_xor(s, 16); s += __shfl_xor(s, 32); ssq[(size_t)row * 32 + u.pn * 4 + wc] = s; }
.LBB0_584:
	v_readlane_b32 s44, v254, 44
	v_readlane_b32 s45, v254, 45
	v_readlane_b32 s46, v255, 10
	v_readlane_b32 s47, v255, 11
	s_andn2_b64 vcc, exec, s[0:1]
	s_mov_b64 s[0:1], -1
	v_bfe_u32 v227, v199, 3, 1
	v_and_b32_e32 v228, 0x77, v199
	v_lshl_add_u32 v229, v227, 4, v200
	v_lshl_add_u32 v225, s42, 8, v228
	v_lshl_or_b32 v226, s55, 8, v229
	v_lshlrev_b32_e32 v224, 13, v225
	v_lshl_add_u32 v224, v226, 2, v224
	v_xor_b32_e32 v230, 16, v188
	v_xor_b32_e32 v231, 32, v188
	v_lshlrev_b32_e32 v230, 2, v230
	v_lshlrev_b32_e32 v231, 2, v231
	v_cmp_ne_u32_e64 s[6:7], 0, v227
	v_lshl_add_u32 v232, s42, 8, v199
	v_lshlrev_b32_e32 v232, 7, v232
	v_bfe_u32 v233, v200, 5, 2
	v_lshl_add_u32 v233, s55, 2, v233
	v_lshl_add_u32 v232, v233, 2, v232
	v_lshrrev_b32_e32 v234, 1, v224
	s_nop 7
	v_mov_b32_e32 v244, v120
	v_mov_b32_e32 v245, v121
	v_mov_b32_e32 v246, v122
	v_mov_b32_e32 v247, v123
	v_mov_b32_dpp v120, v124 row_ror:8 row_mask:0xf bank_mask:0x3
	v_mov_b32_dpp v121, v125 row_ror:8 row_mask:0xf bank_mask:0x3
	v_mov_b32_dpp v122, v126 row_ror:8 row_mask:0xf bank_mask:0x3
	v_mov_b32_dpp v123, v127 row_ror:8 row_mask:0xf bank_mask:0x3
	v_mov_b32_dpp v124, v244 row_ror:8 row_mask:0xf bank_mask:0xc
	v_mov_b32_dpp v125, v245 row_ror:8 row_mask:0xf bank_mask:0xc
	v_mov_b32_dpp v126, v246 row_ror:8 row_mask:0xf bank_mask:0xc
	v_mov_b32_dpp v127, v247 row_ror:8 row_mask:0xf bank_mask:0xc
	v_mov_b32_e32 v244, v112
	v_mov_b32_e32 v245, v113
	v_mov_b32_e32 v246, v114
	v_mov_b32_e32 v247, v115
	v_mov_b32_dpp v112, v116 row_ror:8 row_mask:0xf bank_mask:0x3
	v_mov_b32_dpp v113, v117 row_ror:8 row_mask:0xf bank_mask:0x3
	v_mov_b32_dpp v114, v118 row_ror:8 row_mask:0xf bank_mask:0x3
	v_mov_b32_dpp v115, v119 row_ror:8 row_mask:0xf bank_mask:0x3
	v_mov_b32_dpp v116, v244 row_ror:8 row_mask:0xf bank_mask:0xc
	v_mov_b32_dpp v117, v245 row_ror:8 row_mask:0xf bank_mask:0xc
	v_mov_b32_dpp v118, v246 row_ror:8 row_mask:0xf bank_mask:0xc
	v_mov_b32_dpp v119, v247 row_ror:8 row_mask:0xf bank_mask:0xc
	v_mov_b32_e32 v244, v104
	v_mov_b32_e32 v245, v105
	v_mov_b32_e32 v246, v106
	v_mov_b32_e32 v247, v107
	v_mov_b32_dpp v104, v108 row_ror:8 row_mask:0xf bank_mask:0x3
	v_mov_b32_dpp v105, v109 row_ror:8 row_mask:0xf bank_mask:0x3
	v_mov_b32_dpp v106, v110 row_ror:8 row_mask:0xf bank_mask:0x3
	v_mov_b32_dpp v107, v111 row_ror:8 row_mask:0xf bank_mask:0x3
	v_mov_b32_dpp v108, v244 row_ror:8 row_mask:0xf bank_mask:0xc
	v_mov_b32_dpp v109, v245 row_ror:8 row_mask:0xf bank_mask:0xc
	v_mov_b32_dpp v110, v246 row_ror:8 row_mask:0xf bank_mask:0xc
	v_mov_b32_dpp v111, v247 row_ror:8 row_mask:0xf bank_mask:0xc
	v_mov_b32_e32 v244, v96
	v_mov_b32_e32 v245, v97
	v_mov_b32_e32 v246, v98
	v_mov_b32_e32 v247, v99
	v_mov_b32_dpp v96, v100 row_ror:8 row_mask:0xf bank_mask:0x3
	v_mov_b32_dpp v97, v101 row_ror:8 row_mask:0xf bank_mask:0x3
	v_mov_b32_dpp v98, v102 row_ror:8 row_mask:0xf bank_mask:0x3
	v_mov_b32_dpp v99, v103 row_ror:8 row_mask:0xf bank_mask:0x3
	v_mov_b32_dpp v100, v244 row_ror:8 row_mask:0xf bank_mask:0xc
	v_mov_b32_dpp v101, v245 row_ror:8 row_mask:0xf bank_mask:0xc
	v_mov_b32_dpp v102, v246 row_ror:8 row_mask:0xf bank_mask:0xc
	v_mov_b32_dpp v103, v247 row_ror:8 row_mask:0xf bank_mask:0xc
	v_mov_b32_e32 v244, v88
	v_mov_b32_e32 v245, v89
	v_mov_b32_e32 v246, v90
	v_mov_b32_e32 v247, v91
	v_mov_b32_dpp v88, v92 row_ror:8 row_mask:0xf bank_mask:0x3
	v_mov_b32_dpp v89, v93 row_ror:8 row_mask:0xf bank_mask:0x3
	v_mov_b32_dpp v90, v94 row_ror:8 row_mask:0xf bank_mask:0x3
	v_mov_b32_dpp v91, v95 row_ror:8 row_mask:0xf bank_mask:0x3
	v_mov_b32_dpp v92, v244 row_ror:8 row_mask:0xf bank_mask:0xc
	v_mov_b32_dpp v93, v245 row_ror:8 row_mask:0xf bank_mask:0xc
	v_mov_b32_dpp v94, v246 row_ror:8 row_mask:0xf bank_mask:0xc
	v_mov_b32_dpp v95, v247 row_ror:8 row_mask:0xf bank_mask:0xc
	v_mov_b32_e32 v244, v80
	v_mov_b32_e32 v245, v81
	v_mov_b32_e32 v246, v82
	v_mov_b32_e32 v247, v83
	v_mov_b32_dpp v80, v84 row_ror:8 row_mask:0xf bank_mask:0x3
	v_mov_b32_dpp v81, v85 row_ror:8 row_mask:0xf bank_mask:0x3
	v_mov_b32_dpp v82, v86 row_ror:8 row_mask:0xf bank_mask:0x3
	v_mov_b32_dpp v83, v87 row_ror:8 row_mask:0xf bank_mask:0x3
	v_mov_b32_dpp v84, v244 row_ror:8 row_mask:0xf bank_mask:0xc
	v_mov_b32_dpp v85, v245 row_ror:8 row_mask:0xf bank_mask:0xc
	v_mov_b32_dpp v86, v246 row_ror:8 row_mask:0xf bank_mask:0xc
	v_mov_b32_dpp v87, v247 row_ror:8 row_mask:0xf bank_mask:0xc
	v_mov_b32_e32 v244, v72
	v_mov_b32_e32 v245, v73
	v_mov_b32_e32 v246, v74
	v_mov_b32_e32 v247, v75
	v_mov_b32_dpp v72, v76 row_ror:8 row_mask:0xf bank_mask:0x3
	v_mov_b32_dpp v73, v77 row_ror:8 row_mask:0xf bank_mask:0x3
	v_mov_b32_dpp v74, v78 row_ror:8 row_mask:0xf bank_mask:0x3
	v_mov_b32_dpp v75, v79 row_ror:8 row_mask:0xf bank_mask:0x3
	v_mov_b32_dpp v76, v244 row_ror:8 row_mask:0xf bank_mask:0xc
	v_mov_b32_dpp v77, v245 row_ror:8 row_mask:0xf bank_mask:0xc
	v_mov_b32_dpp v78, v246 row_ror:8 row_mask:0xf bank_mask:0xc
	v_mov_b32_dpp v79, v247 row_ror:8 row_mask:0xf bank_mask:0xc
	v_mov_b32_e32 v244, v64
	v_mov_b32_e32 v245, v65
	v_mov_b32_e32 v246, v66
	v_mov_b32_e32 v247, v67
	v_mov_b32_dpp v64, v68 row_ror:8 row_mask:0xf bank_mask:0x3
	v_mov_b32_dpp v65, v69 row_ror:8 row_mask:0xf bank_mask:0x3
	v_mov_b32_dpp v66, v70 row_ror:8 row_mask:0xf bank_mask:0x3
	v_mov_b32_dpp v67, v71 row_ror:8 row_mask:0xf bank_mask:0x3
	v_mov_b32_dpp v68, v244 row_ror:8 row_mask:0xf bank_mask:0xc
	v_mov_b32_dpp v69, v245 row_ror:8 row_mask:0xf bank_mask:0xc
	v_mov_b32_dpp v70, v246 row_ror:8 row_mask:0xf bank_mask:0xc
	v_mov_b32_dpp v71, v247 row_ror:8 row_mask:0xf bank_mask:0xc
	v_mov_b32_e32 v244, v56
	v_mov_b32_e32 v245, v57
;     __device__ __forceinline__ void operator()(const f32x4 (&acc)[2][2][4][2], const Unit& u, int wr, int wc, int fr, int fq) const {
;     ...
;                 for (int mm = 0; mm < 2; ++mm) { const size_t off = (size_t)(row0 + (ch >> 1) * HALF + ((ch & 1) * 2 + mm) * 16) * ldc + col0;
; #pragma unroll
;                     for (int bj = 0; bj < 2; ++bj)
; #pragma unroll
;                         for (int n = 0; n < 2; ++n) b[ch & 1][mm][bj][n] = *(const f32x4*)(base + off + bj * HALF + n * 16); }
	v_mov_b32_e32 v246, v58
	v_mov_b32_e32 v247, v59
	v_mov_b32_dpp v56, v60 row_ror:8 row_mask:0xf bank_mask:0x3
	v_mov_b32_dpp v57, v61 row_ror:8 row_mask:0xf bank_mask:0x3
	v_mov_b32_dpp v58, v62 row_ror:8 row_mask:0xf bank_mask:0x3
	v_mov_b32_dpp v59, v63 row_ror:8 row_mask:0xf bank_mask:0x3
	v_mov_b32_dpp v60, v244 row_ror:8 row_mask:0xf bank_mask:0xc
	v_mov_b32_dpp v61, v245 row_ror:8 row_mask:0xf bank_mask:0xc
	v_mov_b32_dpp v62, v246 row_ror:8 row_mask:0xf bank_mask:0xc
	v_mov_b32_dpp v63, v247 row_ror:8 row_mask:0xf bank_mask:0xc
	v_mov_b32_e32 v244, v48
	v_mov_b32_e32 v245, v49
	v_mov_b32_e32 v246, v50
	v_mov_b32_e32 v247, v51
	v_mov_b32_dpp v48, v52 row_ror:8 row_mask:0xf bank_mask:0x3
	v_mov_b32_dpp v49, v53 row_ror:8 row_mask:0xf bank_mask:0x3
	v_mov_b32_dpp v50, v54 row_ror:8 row_mask:0xf bank_mask:0x3
	v_mov_b32_dpp v51, v55 row_ror:8 row_mask:0xf bank_mask:0x3
	v_mov_b32_dpp v52, v244 row_ror:8 row_mask:0xf bank_mask:0xc
	v_mov_b32_dpp v53, v245 row_ror:8 row_mask:0xf bank_mask:0xc
	v_mov_b32_dpp v54, v246 row_ror:8 row_mask:0xf bank_mask:0xc
	v_mov_b32_dpp v55, v247 row_ror:8 row_mask:0xf bank_mask:0xc
	v_mov_b32_e32 v244, v40
	v_mov_b32_e32 v245, v41
	v_mov_b32_e32 v246, v42
	v_mov_b32_e32 v247, v43
	v_mov_b32_dpp v40, v44 row_ror:8 row_mask:0xf bank_mask:0x3
	v_mov_b32_dpp v41, v45 row_ror:8 row_mask:0xf bank_mask:0x3
	v_mov_b32_dpp v42, v46 row_ror:8 row_mask:0xf bank_mask:0x3
	v_mov_b32_dpp v43, v47 row_ror:8 row_mask:0xf bank_mask:0x3
	v_mov_b32_dpp v44, v244 row_ror:8 row_mask:0xf bank_mask:0xc
	v_mov_b32_dpp v45, v245 row_ror:8 row_mask:0xf bank_mask:0xc
	v_mov_b32_dpp v46, v246 row_ror:8 row_mask:0xf bank_mask:0xc
	v_mov_b32_dpp v47, v247 row_ror:8 row_mask:0xf bank_mask:0xc
	v_mov_b32_e32 v244, v32
	v_mov_b32_e32 v245, v33
	v_mov_b32_e32 v246, v34
	v_mov_b32_e32 v247, v35
	v_mov_b32_dpp v32, v36 row_ror:8 row_mask:0xf bank_mask:0x3
	v_mov_b32_dpp v33, v37 row_ror:8 row_mask:0xf bank_mask:0x3
	v_mov_b32_dpp v34, v38 row_ror:8 row_mask:0xf bank_mask:0x3
	v_mov_b32_dpp v35, v39 row_ror:8 row_mask:0xf bank_mask:0x3
	v_mov_b32_dpp v36, v244 row_ror:8 row_mask:0xf bank_mask:0xc
	v_mov_b32_dpp v37, v245 row_ror:8 row_mask:0xf bank_mask:0xc
	v_mov_b32_dpp v38, v246 row_ror:8 row_mask:0xf bank_mask:0xc
	v_mov_b32_dpp v39, v247 row_ror:8 row_mask:0xf bank_mask:0xc
	v_mov_b32_e32 v244, v24
	v_mov_b32_e32 v245, v25
	v_mov_b32_e32 v246, v26
	v_mov_b32_e32 v247, v27
	v_mov_b32_dpp v24, v28 row_ror:8 row_mask:0xf bank_mask:0x3
	v_mov_b32_dpp v25, v29 row_ror:8 row_mask:0xf bank_mask:0x3
	v_mov_b32_dpp v26, v30 row_ror:8 row_mask:0xf bank_mask:0x3
	v_mov_b32_dpp v27, v31 row_ror:8 row_mask:0xf bank_mask:0x3
	v_mov_b32_dpp v28, v244 row_ror:8 row_mask:0xf bank_mask:0xc
	v_mov_b32_dpp v29, v245 row_ror:8 row_mask:0xf bank_mask:0xc
	v_mov_b32_dpp v30, v246 row_ror:8 row_mask:0xf bank_mask:0xc
	v_mov_b32_dpp v31, v247 row_ror:8 row_mask:0xf bank_mask:0xc
	v_mov_b32_e32 v244, v16
	v_mov_b32_e32 v245, v17
	v_mov_b32_e32 v246, v18
	v_mov_b32_e32 v247, v19
	v_mov_b32_dpp v16, v20 row_ror:8 row_mask:0xf bank_mask:0x3
	v_mov_b32_dpp v17, v21 row_ror:8 row_mask:0xf bank_mask:0x3
	v_mov_b32_dpp v18, v22 row_ror:8 row_mask:0xf bank_mask:0x3
	v_mov_b32_dpp v19, v23 row_ror:8 row_mask:0xf bank_mask:0x3
	v_mov_b32_dpp v20, v244 row_ror:8 row_mask:0xf bank_mask:0xc
	v_mov_b32_dpp v21, v245 row_ror:8 row_mask:0xf bank_mask:0xc
	v_mov_b32_dpp v22, v246 row_ror:8 row_mask:0xf bank_mask:0xc
	v_mov_b32_dpp v23, v247 row_ror:8 row_mask:0xf bank_mask:0xc
	v_mov_b32_e32 v244, v8
	v_mov_b32_e32 v245, v9
	v_mov_b32_e32 v246, v10
	v_mov_b32_e32 v247, v11
	v_mov_b32_dpp v8, v12 row_ror:8 row_mask:0xf bank_mask:0x3
	v_mov_b32_dpp v9, v13 row_ror:8 row_mask:0xf bank_mask:0x3
	v_mov_b32_dpp v10, v14 row_ror:8 row_mask:0xf bank_mask:0x3
	v_mov_b32_dpp v11, v15 row_ror:8 row_mask:0xf bank_mask:0x3
	v_mov_b32_dpp v12, v244 row_ror:8 row_mask:0xf bank_mask:0xc
	v_mov_b32_dpp v13, v245 row_ror:8 row_mask:0xf bank_mask:0xc
	v_mov_b32_dpp v14, v246 row_ror:8 row_mask:0xf bank_mask:0xc
	v_mov_b32_dpp v15, v247 row_ror:8 row_mask:0xf bank_mask:0xc
	v_mov_b32_e32 v244, v0
	v_mov_b32_e32 v245, v1
	v_mov_b32_e32 v246, v2
	v_mov_b32_e32 v247, v3
	v_mov_b32_dpp v0, v4 row_ror:8 row_mask:0xf bank_mask:0x3
	v_mov_b32_dpp v1, v5 row_ror:8 row_mask:0xf bank_mask:0x3
	v_mov_b32_dpp v2, v6 row_ror:8 row_mask:0xf bank_mask:0x3
	v_mov_b32_dpp v3, v7 row_ror:8 row_mask:0xf bank_mask:0x3
	v_mov_b32_dpp v4, v244 row_ror:8 row_mask:0xf bank_mask:0xc
	v_mov_b32_dpp v5, v245 row_ror:8 row_mask:0xf bank_mask:0xc
	v_mov_b32_dpp v6, v246 row_ror:8 row_mask:0xf bank_mask:0xc
	v_mov_b32_dpp v7, v247 row_ror:8 row_mask:0xf bank_mask:0xc
	v_add_u32_e32 v216, 0x0, v224
	v_add_u32_e32 v217, 0x10000, v224
	v_add_u32_e32 v218, 0x20000, v224
	v_add_u32_e32 v219, 0x30000, v224
	global_load_dwordx4 v[128:131], v216, s[88:89]
	global_load_dwordx4 v[132:135], v216, s[88:89] offset:512
	global_load_dwordx4 v[136:139], v217, s[88:89]
	global_load_dwordx4 v[140:143], v217, s[88:89] offset:512
	global_load_dwordx4 v[144:147], v218, s[88:89]
	global_load_dwordx4 v[148:151], v218, s[88:89] offset:512
	global_load_dwordx4 v[152:155], v219, s[88:89]
	global_load_dwordx4 v[156:159], v219, s[88:89] offset:512
	v_add_u32_e32 v220, 0x40000, v224
	v_add_u32_e32 v221, 0x50000, v224
	v_add_u32_e32 v222, 0x60000, v224
	v_add_u32_e32 v223, 0x70000, v224
	global_load_dwordx4 v[164:167], v220, s[88:89]
	global_load_dwordx4 v[168:171], v220, s[88:89] offset:512
	global_load_dwordx4 v[172:175], v221, s[88:89]
	global_load_dwordx4 v[176:179], v221, s[88:89] offset:512
	global_load_dwordx4 v[180:183], v222, s[88:89]
	global_load_dwordx4 v[184:187], v222, s[88:89] offset:512
	global_load_dwordx4 v[208:211], v223, s[88:89]
	global_load_dwordx4 v[212:215], v223, s[88:89] offset:512
	s_waitcnt vmcnt(15)
; __device__ __forceinline__ unsigned cvt_pk_bf16(float lo, float hi) { typedef float f2_t __attribute__((ext_vector_type(2))); typedef __bf16 b2_t __attribute__((ext_vector_type(2))); const f2_t v = {lo, hi}; return __builtin_bit_cast(unsigned, __builtin_convertvector(v, b2_t)); }
;     __device__ __forceinline__ void operator()(const f32x4 (&acc)[2][2][4][2], const Unit& u, int wr, int wc, int fr, int fq) const {
;     ...
;                 for (int mm = 0; mm < 2; ++mm) { const size_t off = (size_t)(row0 + (ch >> 1) * HALF + ((ch & 1) * 2 + mm) * 16) * ldc + col0;
; #pragma unroll
;                     for (int bj = 0; bj < 2; ++bj)
; #pragma unroll
;                         for (int n = 0; n < 2; ++n) b[ch & 1][mm][bj][n] = *(const f32x4*)(base + off + bj * HALF + n * 16); }
;             }
;             asm volatile("" ::: "memory");
;             if (ch > 0) {
;                 const int pc = ch - 1, ai = pc >> 1;
; #pragma unroll
;                 for (int mm = 0; mm < 2; ++mm) { const int m = (pc & 1) * 2 + mm, row = row0 + ai * HALF + m * 16; const size_t off = (size_t)row * ldc + col0;
;                     float s = 0.f;
; #pragma unroll
;                     for (int bj = 0; bj < 2; ++bj)
; #pragma unroll
;                         for (int n = 0; n < 2; ++n) {
;                             const f32x4 o = b[pc & 1][mm][bj][n] + acc[ai][bj][m][n] * scale;
;                             *(f32x4*)(out + off + bj * HALF + n * 16) = o;
;                             if (NORM) { s += (o[0] * o[0] + o[1] * o[1]) + (o[2] * o[2] + o[3] * o[3]);
;                                 u32x2 w; w.x = cvt_pk_bf16(o[0], o[1]); w.y = cvt_pk_bf16(o[2], o[3]); *(u32x2*)(xb + off + bj * HALF + n * 16) = w; }
;                         }
;                     if (NORM) { s += __shfl_xor(s, 16); s += __shfl_xor(s, 32); ssq[(size_t)row * 32 + u.pn * 4 + wc] = s; }
	v_pk_add_f32 v[124:125], v[124:125], v[128:129]
	v_pk_add_f32 v[126:127], v[126:127], v[130:131]
	s_waitcnt vmcnt(14)
	v_pk_add_f32 v[116:117], v[116:117], v[132:133]
	v_pk_add_f32 v[118:119], v[118:119], v[134:135]
	s_waitcnt vmcnt(13)
	v_pk_add_f32 v[120:121], v[120:121], v[136:137]
	v_pk_add_f32 v[122:123], v[122:123], v[138:139]
	s_waitcnt vmcnt(12)
	v_pk_add_f32 v[112:113], v[112:113], v[140:141]
	v_pk_add_f32 v[114:115], v[114:115], v[142:143]
	s_waitcnt vmcnt(11)
	v_pk_add_f32 v[108:109], v[108:109], v[144:145]
	v_pk_add_f32 v[110:111], v[110:111], v[146:147]
	s_waitcnt vmcnt(10)
	v_pk_add_f32 v[100:101], v[100:101], v[148:149]
	v_pk_add_f32 v[102:103], v[102:103], v[150:151]
	s_waitcnt vmcnt(9)
	v_pk_add_f32 v[104:105], v[104:105], v[152:153]
	v_pk_add_f32 v[106:107], v[106:107], v[154:155]
	s_waitcnt vmcnt(8)
	v_pk_add_f32 v[96:97], v[96:97], v[156:157]
	v_pk_add_f32 v[98:99], v[98:99], v[158:159]
	global_store_dwordx4 v216, v[124:127], s[88:89]
	global_store_dwordx4 v216, v[116:119], s[88:89] offset:512
	global_store_dwordx4 v217, v[120:123], s[88:89]
	global_store_dwordx4 v217, v[112:115], s[88:89] offset:512
	global_store_dwordx4 v218, v[108:111], s[88:89]
	global_store_dwordx4 v218, v[100:103], s[88:89] offset:512
	global_store_dwordx4 v219, v[104:107], s[88:89]
	global_store_dwordx4 v219, v[96:99], s[88:89] offset:512
	v_mul_f32_e32 v235, v124, v124
	v_fmac_f32_e32 v235, v125, v125
	v_fmac_f32_e32 v235, v126, v126
	v_fmac_f32_e32 v235, v127, v127
	v_fmac_f32_e32 v235, v116, v116
	v_fmac_f32_e32 v235, v117, v117
	v_fmac_f32_e32 v235, v118, v118
	v_fmac_f32_e32 v235, v119, v119
	v_mul_f32_e32 v236, v120, v120
	v_fmac_f32_e32 v236, v121, v121
	v_fmac_f32_e32 v236, v122, v122
	v_fmac_f32_e32 v236, v123, v123
	v_fmac_f32_e32 v236, v112, v112
	v_fmac_f32_e32 v236, v113, v113
	v_fmac_f32_e32 v236, v114, v114
	v_fmac_f32_e32 v236, v115, v115
	v_mul_f32_e32 v237, v108, v108
	v_fmac_f32_e32 v237, v109, v109
	v_fmac_f32_e32 v237, v110, v110
	v_fmac_f32_e32 v237, v111, v111
	v_fmac_f32_e32 v237, v100, v100
	v_fmac_f32_e32 v237, v101, v101
	v_fmac_f32_e32 v237, v102, v102
	v_fmac_f32_e32 v237, v103, v103
	v_mul_f32_e32 v238, v104, v104
	v_fmac_f32_e32 v238, v105, v105
	v_fmac_f32_e32 v238, v106, v106
	v_fmac_f32_e32 v238, v107, v107
	v_fmac_f32_e32 v238, v96, v96
	v_fmac_f32_e32 v238, v97, v97
	v_fmac_f32_e32 v238, v98, v98
	v_fmac_f32_e32 v238, v99, v99
	v_cvt_pk_bf16_f32 v128, v124, v125
	v_cvt_pk_bf16_f32 v129, v126, v127
	v_cvt_pk_bf16_f32 v132, v116, v117
	v_cvt_pk_bf16_f32 v133, v118, v119
	v_cvt_pk_bf16_f32 v136, v120, v121
	v_cvt_pk_bf16_f32 v137, v122, v123
	v_cvt_pk_bf16_f32 v140, v112, v113
	v_cvt_pk_bf16_f32 v141, v114, v115
	v_cvt_pk_bf16_f32 v144, v108, v109
	v_cvt_pk_bf16_f32 v145, v110, v111
	v_cvt_pk_bf16_f32 v148, v100, v101
	v_cvt_pk_bf16_f32 v149, v102, v103
	v_cvt_pk_bf16_f32 v152, v104, v105
	v_cvt_pk_bf16_f32 v153, v106, v107
	v_cvt_pk_bf16_f32 v156, v96, v97
	v_cvt_pk_bf16_f32 v157, v98, v99
	v_add_u32_e32 v239, 0x0, v234
	v_add_u32_e32 v190, 0x8000, v234
	v_add_u32_e32 v191, 0x10000, v234
	v_add_u32_e32 v192, 0x18000, v234
	global_store_dwordx2 v239, v[128:129], s[44:45]
	global_store_dwordx2 v239, v[132:133], s[44:45] offset:256
	global_store_dwordx2 v190, v[136:137], s[44:45]
	global_store_dwordx2 v190, v[140:141], s[44:45] offset:256
	global_store_dwordx2 v191, v[144:145], s[44:45]
	global_store_dwordx2 v191, v[148:149], s[44:45] offset:256
	global_store_dwordx2 v192, v[152:153], s[44:45]
	global_store_dwordx2 v192, v[156:157], s[44:45] offset:256
	ds_bpermute_b32 v193, v230, v235
	ds_bpermute_b32 v194, v230, v236
	ds_bpermute_b32 v195, v230, v237
	ds_bpermute_b32 v207, v230, v238
	s_waitcnt lgkmcnt(0)
	v_add_f32_e32 v235, v235, v193
	v_add_f32_e32 v236, v236, v194
	v_add_f32_e32 v237, v237, v195
	v_add_f32_e32 v238, v238, v207
	ds_bpermute_b32 v193, v231, v235
	ds_bpermute_b32 v194, v231, v236
	ds_bpermute_b32 v195, v231, v237
	ds_bpermute_b32 v207, v231, v238
	s_waitcnt lgkmcnt(0)
	v_add_f32_e32 v235, v235, v193
	v_add_f32_e32 v236, v236, v194
	v_add_f32_e32 v237, v237, v195
	v_add_f32_e32 v238, v238, v207
	s_nop 1
	v_add_f32_dpp v193, v235, v235 row_ror:8 row_mask:0xf bank_mask:0xf
	v_add_f32_dpp v194, v236, v236 row_ror:8 row_mask:0xf bank_mask:0xf
	v_add_f32_dpp v195, v237, v237 row_ror:8 row_mask:0xf bank_mask:0xf
	v_add_f32_dpp v207, v238, v238 row_ror:8 row_mask:0xf bank_mask:0xf
	v_cndmask_b32_e64 v248, v193, v194, s[6:7]
	v_add_u32_e32 v250, 0x0, v232
	v_cndmask_b32_e64 v249, v195, v207, s[6:7]
	v_add_u32_e32 v251, 0x800, v232
	global_store_dword v250, v248, s[46:47]
	global_store_dword v251, v249, s[46:47]
	v_add_u32_e32 v216, 0x100000, v224
	v_add_u32_e32 v217, 0x110000, v224
	v_add_u32_e32 v218, 0x120000, v224
	v_add_u32_e32 v219, 0x130000, v224
	global_load_dwordx4 v[128:131], v216, s[88:89]
	global_load_dwordx4 v[132:135], v216, s[88:89] offset:512
	global_load_dwordx4 v[136:139], v217, s[88:89]
	global_load_dwordx4 v[140:143], v217, s[88:89] offset:512
	global_load_dwordx4 v[144:147], v218, s[88:89]
	global_load_dwordx4 v[148:151], v218, s[88:89] offset:512
	global_load_dwordx4 v[152:155], v219, s[88:89]
	global_load_dwordx4 v[156:159], v219, s[88:89] offset:512
	s_waitcnt vmcnt(33)
	v_pk_add_f32 v[92:93], v[92:93], v[164:165]
	v_pk_add_f32 v[94:95], v[94:95], v[166:167]
	s_waitcnt vmcnt(32)
	v_pk_add_f32 v[84:85], v[84:85], v[168:169]
	v_pk_add_f32 v[86:87], v[86:87], v[170:171]
	s_waitcnt vmcnt(31)
	v_pk_add_f32 v[88:89], v[88:89], v[172:173]
	v_pk_add_f32 v[90:91], v[90:91], v[174:175]
	s_waitcnt vmcnt(30)
	v_pk_add_f32 v[80:81], v[80:81], v[176:177]
	v_pk_add_f32 v[82:83], v[82:83], v[178:179]
	s_waitcnt vmcnt(29)
; __device__ __forceinline__ unsigned cvt_pk_bf16(float lo, float hi) { typedef float f2_t __attribute__((ext_vector_type(2))); typedef __bf16 b2_t __attribute__((ext_vector_type(2))); const f2_t v = {lo, hi}; return __builtin_bit_cast(unsigned, __builtin_convertvector(v, b2_t)); }
;     __device__ __forceinline__ void operator()(const f32x4 (&acc)[2][2][4][2], const Unit& u, int wr, int wc, int fr, int fq) const {
;     ...
;                 for (int mm = 0; mm < 2; ++mm) { const size_t off = (size_t)(row0 + (ch >> 1) * HALF + ((ch & 1) * 2 + mm) * 16) * ldc + col0;
; #pragma unroll
;                     for (int bj = 0; bj < 2; ++bj)
; #pragma unroll
;                         for (int n = 0; n < 2; ++n) b[ch & 1][mm][bj][n] = *(const f32x4*)(base + off + bj * HALF + n * 16); }
;             }
;             asm volatile("" ::: "memory");
;             if (ch > 0) {
;                 const int pc = ch - 1, ai = pc >> 1;
; #pragma unroll
;                 for (int mm = 0; mm < 2; ++mm) { const int m = (pc & 1) * 2 + mm, row = row0 + ai * HALF + m * 16; const size_t off = (size_t)row * ldc + col0;
;                     float s = 0.f;
; #pragma unroll
;                     for (int bj = 0; bj < 2; ++bj)
; #pragma unroll
;                         for (int n = 0; n < 2; ++n) {
;                             const f32x4 o = b[pc & 1][mm][bj][n] + acc[ai][bj][m][n] * scale;
;                             *(f32x4*)(out + off + bj * HALF + n * 16) = o;
;                             if (NORM) { s += (o[0] * o[0] + o[1] * o[1]) + (o[2] * o[2] + o[3] * o[3]);
;                                 u32x2 w; w.x = cvt_pk_bf16(o[0], o[1]); w.y = cvt_pk_bf16(o[2], o[3]); *(u32x2*)(xb + off + bj * HALF + n * 16) = w; }
;                         }
;                     if (NORM) { s += __shfl_xor(s, 16); s += __shfl_xor(s, 32); ssq[(size_t)row * 32 + u.pn * 4 + wc] = s; }
	v_pk_add_f32 v[76:77], v[76:77], v[180:181]
	v_pk_add_f32 v[78:79], v[78:79], v[182:183]
	s_waitcnt vmcnt(28)
	v_pk_add_f32 v[68:69], v[68:69], v[184:185]
	v_pk_add_f32 v[70:71], v[70:71], v[186:187]
	s_waitcnt vmcnt(27)
	v_pk_add_f32 v[72:73], v[72:73], v[208:209]
	v_pk_add_f32 v[74:75], v[74:75], v[210:211]
	s_waitcnt vmcnt(26)
	v_pk_add_f32 v[64:65], v[64:65], v[212:213]
	v_pk_add_f32 v[66:67], v[66:67], v[214:215]
	global_store_dwordx4 v220, v[92:95], s[88:89]
	global_store_dwordx4 v220, v[84:87], s[88:89] offset:512
	global_store_dwordx4 v221, v[88:91], s[88:89]
	global_store_dwordx4 v221, v[80:83], s[88:89] offset:512
	global_store_dwordx4 v222, v[76:79], s[88:89]
	global_store_dwordx4 v222, v[68:71], s[88:89] offset:512
	global_store_dwordx4 v223, v[72:75], s[88:89]
	global_store_dwordx4 v223, v[64:67], s[88:89] offset:512
	v_mul_f32_e32 v235, v92, v92
	v_fmac_f32_e32 v235, v93, v93
	v_fmac_f32_e32 v235, v94, v94
	v_fmac_f32_e32 v235, v95, v95
	v_fmac_f32_e32 v235, v84, v84
	v_fmac_f32_e32 v235, v85, v85
	v_fmac_f32_e32 v235, v86, v86
	v_fmac_f32_e32 v235, v87, v87
	v_mul_f32_e32 v236, v88, v88
	v_fmac_f32_e32 v236, v89, v89
	v_fmac_f32_e32 v236, v90, v90
	v_fmac_f32_e32 v236, v91, v91
	v_fmac_f32_e32 v236, v80, v80
	v_fmac_f32_e32 v236, v81, v81
	v_fmac_f32_e32 v236, v82, v82
	v_fmac_f32_e32 v236, v83, v83
	v_mul_f32_e32 v237, v76, v76
	v_fmac_f32_e32 v237, v77, v77
	v_fmac_f32_e32 v237, v78, v78
	v_fmac_f32_e32 v237, v79, v79
	v_fmac_f32_e32 v237, v68, v68
	v_fmac_f32_e32 v237, v69, v69
	v_fmac_f32_e32 v237, v70, v70
	v_fmac_f32_e32 v237, v71, v71
	v_mul_f32_e32 v238, v72, v72
	v_fmac_f32_e32 v238, v73, v73
	v_fmac_f32_e32 v238, v74, v74
	v_fmac_f32_e32 v238, v75, v75
	v_fmac_f32_e32 v238, v64, v64
	v_fmac_f32_e32 v238, v65, v65
	v_fmac_f32_e32 v238, v66, v66
	v_fmac_f32_e32 v238, v67, v67
	v_cvt_pk_bf16_f32 v164, v92, v93
	v_cvt_pk_bf16_f32 v165, v94, v95
	v_cvt_pk_bf16_f32 v168, v84, v85
	v_cvt_pk_bf16_f32 v169, v86, v87
	v_cvt_pk_bf16_f32 v172, v88, v89
	v_cvt_pk_bf16_f32 v173, v90, v91
	v_cvt_pk_bf16_f32 v176, v80, v81
	v_cvt_pk_bf16_f32 v177, v82, v83
	v_cvt_pk_bf16_f32 v180, v76, v77
	v_cvt_pk_bf16_f32 v181, v78, v79
	v_cvt_pk_bf16_f32 v184, v68, v69
	v_cvt_pk_bf16_f32 v185, v70, v71
	v_cvt_pk_bf16_f32 v208, v72, v73
	v_cvt_pk_bf16_f32 v209, v74, v75
	v_cvt_pk_bf16_f32 v212, v64, v65
	v_cvt_pk_bf16_f32 v213, v66, v67
	v_add_u32_e32 v239, 0x20000, v234
	v_add_u32_e32 v190, 0x28000, v234
	v_add_u32_e32 v191, 0x30000, v234
	v_add_u32_e32 v192, 0x38000, v234
	global_store_dwordx2 v239, v[164:165], s[44:45]
	global_store_dwordx2 v239, v[168:169], s[44:45] offset:256
	global_store_dwordx2 v190, v[172:173], s[44:45]
	global_store_dwordx2 v190, v[176:177], s[44:45] offset:256
	global_store_dwordx2 v191, v[180:181], s[44:45]
	global_store_dwordx2 v191, v[184:185], s[44:45] offset:256
	global_store_dwordx2 v192, v[208:209], s[44:45]
	global_store_dwordx2 v192, v[212:213], s[44:45] offset:256
	ds_bpermute_b32 v193, v230, v235
	ds_bpermute_b32 v194, v230, v236
	ds_bpermute_b32 v195, v230, v237
	ds_bpermute_b32 v207, v230, v238
	s_waitcnt lgkmcnt(0)
	v_add_f32_e32 v235, v235, v193
	v_add_f32_e32 v236, v236, v194
	v_add_f32_e32 v237, v237, v195
	v_add_f32_e32 v238, v238, v207
	ds_bpermute_b32 v193, v231, v235
	ds_bpermute_b32 v194, v231, v236
	ds_bpermute_b32 v195, v231, v237
	ds_bpermute_b32 v207, v231, v238
	s_waitcnt lgkmcnt(0)
	v_add_f32_e32 v235, v235, v193
	v_add_f32_e32 v236, v236, v194
	v_add_f32_e32 v237, v237, v195
	v_add_f32_e32 v238, v238, v207
	s_nop 1
	v_add_f32_dpp v193, v235, v235 row_ror:8 row_mask:0xf bank_mask:0xf
	v_add_f32_dpp v194, v236, v236 row_ror:8 row_mask:0xf bank_mask:0xf
	v_add_f32_dpp v195, v237, v237 row_ror:8 row_mask:0xf bank_mask:0xf
	v_add_f32_dpp v207, v238, v238 row_ror:8 row_mask:0xf bank_mask:0xf
	v_cndmask_b32_e64 v248, v193, v194, s[6:7]
	v_add_u32_e32 v250, 0x1000, v232
	v_cndmask_b32_e64 v249, v195, v207, s[6:7]
	v_add_u32_e32 v251, 0x1800, v232
	global_store_dword v250, v248, s[46:47]
	global_store_dword v251, v249, s[46:47]
	v_add_u32_e32 v220, 0x140000, v224
	v_add_u32_e32 v221, 0x150000, v224
	v_add_u32_e32 v222, 0x160000, v224
	v_add_u32_e32 v223, 0x170000, v224
	global_load_dwordx4 v[164:167], v220, s[88:89]
	global_load_dwordx4 v[168:171], v220, s[88:89] offset:512
	global_load_dwordx4 v[172:175], v221, s[88:89]
	global_load_dwordx4 v[176:179], v221, s[88:89] offset:512
	global_load_dwordx4 v[180:183], v222, s[88:89]
	global_load_dwordx4 v[184:187], v222, s[88:89] offset:512
	global_load_dwordx4 v[208:211], v223, s[88:89]
	global_load_dwordx4 v[212:215], v223, s[88:89] offset:512
	s_waitcnt vmcnt(33)
	v_pk_add_f32 v[60:61], v[60:61], v[128:129]
	v_pk_add_f32 v[62:63], v[62:63], v[130:131]
	s_waitcnt vmcnt(32)
	v_pk_add_f32 v[52:53], v[52:53], v[132:133]
	v_pk_add_f32 v[54:55], v[54:55], v[134:135]
	s_waitcnt vmcnt(31)
	v_pk_add_f32 v[56:57], v[56:57], v[136:137]
	v_pk_add_f32 v[58:59], v[58:59], v[138:139]
	s_waitcnt vmcnt(30)
	v_pk_add_f32 v[48:49], v[48:49], v[140:141]
	v_pk_add_f32 v[50:51], v[50:51], v[142:143]
	s_waitcnt vmcnt(29)
	v_pk_add_f32 v[44:45], v[44:45], v[144:145]
	v_pk_add_f32 v[46:47], v[46:47], v[146:147]
	s_waitcnt vmcnt(28)
	v_pk_add_f32 v[36:37], v[36:37], v[148:149]
	v_pk_add_f32 v[38:39], v[38:39], v[150:151]
	s_waitcnt vmcnt(27)
	v_pk_add_f32 v[40:41], v[40:41], v[152:153]
	v_pk_add_f32 v[42:43], v[42:43], v[154:155]
	s_waitcnt vmcnt(26)
; __device__ __forceinline__ unsigned cvt_pk_bf16(float lo, float hi) { typedef float f2_t __attribute__((ext_vector_type(2))); typedef __bf16 b2_t __attribute__((ext_vector_type(2))); const f2_t v = {lo, hi}; return __builtin_bit_cast(unsigned, __builtin_convertvector(v, b2_t)); }
;     __device__ __forceinline__ void operator()(const f32x4 (&acc)[2][2][4][2], const Unit& u, int wr, int wc, int fr, int fq) const {
;     ...
;                 for (int mm = 0; mm < 2; ++mm) { const size_t off = (size_t)(row0 + (ch >> 1) * HALF + ((ch & 1) * 2 + mm) * 16) * ldc + col0;
; #pragma unroll
;                     for (int bj = 0; bj < 2; ++bj)
; #pragma unroll
;                         for (int n = 0; n < 2; ++n) b[ch & 1][mm][bj][n] = *(const f32x4*)(base + off + bj * HALF + n * 16); }
;             }
;             asm volatile("" ::: "memory");
;             if (ch > 0) {
;                 const int pc = ch - 1, ai = pc >> 1;
; #pragma unroll
;                 for (int mm = 0; mm < 2; ++mm) { const int m = (pc & 1) * 2 + mm, row = row0 + ai * HALF + m * 16; const size_t off = (size_t)row * ldc + col0;
;                     float s = 0.f;
; #pragma unroll
;                     for (int bj = 0; bj < 2; ++bj)
; #pragma unroll
;                         for (int n = 0; n < 2; ++n) {
;                             const f32x4 o = b[pc & 1][mm][bj][n] + acc[ai][bj][m][n] * scale;
;                             *(f32x4*)(out + off + bj * HALF + n * 16) = o;
;                             if (NORM) { s += (o[0] * o[0] + o[1] * o[1]) + (o[2] * o[2] + o[3] * o[3]);
;                                 u32x2 w; w.x = cvt_pk_bf16(o[0], o[1]); w.y = cvt_pk_bf16(o[2], o[3]); *(u32x2*)(xb + off + bj * HALF + n * 16) = w; }
;                         }
;                     if (NORM) { s += __shfl_xor(s, 16); s += __shfl_xor(s, 32); ssq[(size_t)row * 32 + u.pn * 4 + wc] = s; }
	v_pk_add_f32 v[32:33], v[32:33], v[156:157]
	v_pk_add_f32 v[34:35], v[34:35], v[158:159]
	global_store_dwordx4 v216, v[60:63], s[88:89]
	global_store_dwordx4 v216, v[52:55], s[88:89] offset:512
	global_store_dwordx4 v217, v[56:59], s[88:89]
	global_store_dwordx4 v217, v[48:51], s[88:89] offset:512
	global_store_dwordx4 v218, v[44:47], s[88:89]
	global_store_dwordx4 v218, v[36:39], s[88:89] offset:512
	global_store_dwordx4 v219, v[40:43], s[88:89]
	global_store_dwordx4 v219, v[32:35], s[88:89] offset:512
	v_mul_f32_e32 v235, v60, v60
	v_fmac_f32_e32 v235, v61, v61
	v_fmac_f32_e32 v235, v62, v62
	v_fmac_f32_e32 v235, v63, v63
	v_fmac_f32_e32 v235, v52, v52
	v_fmac_f32_e32 v235, v53, v53
	v_fmac_f32_e32 v235, v54, v54
	v_fmac_f32_e32 v235, v55, v55
	v_mul_f32_e32 v236, v56, v56
	v_fmac_f32_e32 v236, v57, v57
	v_fmac_f32_e32 v236, v58, v58
	v_fmac_f32_e32 v236, v59, v59
	v_fmac_f32_e32 v236, v48, v48
	v_fmac_f32_e32 v236, v49, v49
	v_fmac_f32_e32 v236, v50, v50
	v_fmac_f32_e32 v236, v51, v51
	v_mul_f32_e32 v237, v44, v44
	v_fmac_f32_e32 v237, v45, v45
	v_fmac_f32_e32 v237, v46, v46
	v_fmac_f32_e32 v237, v47, v47
	v_fmac_f32_e32 v237, v36, v36
	v_fmac_f32_e32 v237, v37, v37
	v_fmac_f32_e32 v237, v38, v38
	v_fmac_f32_e32 v237, v39, v39
	v_mul_f32_e32 v238, v40, v40
	v_fmac_f32_e32 v238, v41, v41
	v_fmac_f32_e32 v238, v42, v42
	v_fmac_f32_e32 v238, v43, v43
	v_fmac_f32_e32 v238, v32, v32
	v_fmac_f32_e32 v238, v33, v33
	v_fmac_f32_e32 v238, v34, v34
	v_fmac_f32_e32 v238, v35, v35
	v_cvt_pk_bf16_f32 v128, v60, v61
	v_cvt_pk_bf16_f32 v129, v62, v63
	v_cvt_pk_bf16_f32 v132, v52, v53
	v_cvt_pk_bf16_f32 v133, v54, v55
	v_cvt_pk_bf16_f32 v136, v56, v57
	v_cvt_pk_bf16_f32 v137, v58, v59
	v_cvt_pk_bf16_f32 v140, v48, v49
	v_cvt_pk_bf16_f32 v141, v50, v51
	v_cvt_pk_bf16_f32 v144, v44, v45
	v_cvt_pk_bf16_f32 v145, v46, v47
	v_cvt_pk_bf16_f32 v148, v36, v37
	v_cvt_pk_bf16_f32 v149, v38, v39
	v_cvt_pk_bf16_f32 v152, v40, v41
	v_cvt_pk_bf16_f32 v153, v42, v43
	v_cvt_pk_bf16_f32 v156, v32, v33
	v_cvt_pk_bf16_f32 v157, v34, v35
	v_add_u32_e32 v239, 0x80000, v234
	v_add_u32_e32 v190, 0x88000, v234
	v_add_u32_e32 v191, 0x90000, v234
	v_add_u32_e32 v192, 0x98000, v234
	global_store_dwordx2 v239, v[128:129], s[44:45]
	global_store_dwordx2 v239, v[132:133], s[44:45] offset:256
	global_store_dwordx2 v190, v[136:137], s[44:45]
	global_store_dwordx2 v190, v[140:141], s[44:45] offset:256
	global_store_dwordx2 v191, v[144:145], s[44:45]
	global_store_dwordx2 v191, v[148:149], s[44:45] offset:256
	global_store_dwordx2 v192, v[152:153], s[44:45]
	global_store_dwordx2 v192, v[156:157], s[44:45] offset:256
	ds_bpermute_b32 v193, v230, v235
	ds_bpermute_b32 v194, v230, v236
	ds_bpermute_b32 v195, v230, v237
	ds_bpermute_b32 v207, v230, v238
	s_waitcnt lgkmcnt(0)
	v_add_f32_e32 v235, v235, v193
	v_add_f32_e32 v236, v236, v194
	v_add_f32_e32 v237, v237, v195
	v_add_f32_e32 v238, v238, v207
	ds_bpermute_b32 v193, v231, v235
	ds_bpermute_b32 v194, v231, v236
	ds_bpermute_b32 v195, v231, v237
	ds_bpermute_b32 v207, v231, v238
	s_waitcnt lgkmcnt(0)
	v_add_f32_e32 v235, v235, v193
	v_add_f32_e32 v236, v236, v194
	v_add_f32_e32 v237, v237, v195
	v_add_f32_e32 v238, v238, v207
	s_nop 1
	v_add_f32_dpp v193, v235, v235 row_ror:8 row_mask:0xf bank_mask:0xf
	v_add_f32_dpp v194, v236, v236 row_ror:8 row_mask:0xf bank_mask:0xf
	v_add_f32_dpp v195, v237, v237 row_ror:8 row_mask:0xf bank_mask:0xf
	v_add_f32_dpp v207, v238, v238 row_ror:8 row_mask:0xf bank_mask:0xf
	v_cndmask_b32_e64 v248, v193, v194, s[6:7]
	v_add_u32_e32 v250, 0x4000, v232
	v_cndmask_b32_e64 v249, v195, v207, s[6:7]
	v_add_u32_e32 v251, 0x4800, v232
	global_store_dword v250, v248, s[46:47]
	global_store_dword v251, v249, s[46:47]
	s_waitcnt vmcnt(25)
	v_pk_add_f32 v[28:29], v[28:29], v[164:165]
	v_pk_add_f32 v[30:31], v[30:31], v[166:167]
	s_waitcnt vmcnt(24)
	v_pk_add_f32 v[20:21], v[20:21], v[168:169]
	v_pk_add_f32 v[22:23], v[22:23], v[170:171]
	s_waitcnt vmcnt(23)
	v_pk_add_f32 v[24:25], v[24:25], v[172:173]
	v_pk_add_f32 v[26:27], v[26:27], v[174:175]
	s_waitcnt vmcnt(22)
	v_pk_add_f32 v[16:17], v[16:17], v[176:177]
	v_pk_add_f32 v[18:19], v[18:19], v[178:179]
	s_waitcnt vmcnt(21)
; __device__ __forceinline__ unsigned cvt_pk_bf16(float lo, float hi) { typedef float f2_t __attribute__((ext_vector_type(2))); typedef __bf16 b2_t __attribute__((ext_vector_type(2))); const f2_t v = {lo, hi}; return __builtin_bit_cast(unsigned, __builtin_convertvector(v, b2_t)); }
; #define PG8_BAR __builtin_amdgcn_s_barrier()
; template <class Epi, class Sched, bool ALIGN_EPI = false, bool SP2 = false>
; __device__ __forceinline__ void gemm_phase(PG8_LAS unsigned char* lds, const Gemm g, const Sched& S, const Epi& E) {
;     ...
;         if constexpr (!Epi::AFTER_DRAIN) { E(acc, cur, wr, wc, fr, fq); S.done(cur); }
;         if (!has_next) break;
;         cur = nxt; cA = nA; cB = nB; ++ui;
;         if constexpr (ALIGN_EPI) { if (wr == 1) PG8_BAR; }
;     __device__ __forceinline__ void operator()(const f32x4 (&acc)[2][2][4][2], const Unit& u, int wr, int wc, int fr, int fq) const {
;     ...
;                 for (int mm = 0; mm < 2; ++mm) { const size_t off = (size_t)(row0 + (ch >> 1) * HALF + ((ch & 1) * 2 + mm) * 16) * ldc + col0;
; #pragma unroll
;                     for (int bj = 0; bj < 2; ++bj)
; #pragma unroll
;                         for (int n = 0; n < 2; ++n) b[ch & 1][mm][bj][n] = *(const f32x4*)(base + off + bj * HALF + n * 16); }
;             }
;             asm volatile("" ::: "memory");
;             if (ch > 0) {
;                 const int pc = ch - 1, ai = pc >> 1;
; #pragma unroll
;                 for (int mm = 0; mm < 2; ++mm) { const int m = (pc & 1) * 2 + mm, row = row0 + ai * HALF + m * 16; const size_t off = (size_t)row * ldc + col0;
;                     float s = 0.f;
; #pragma unroll
;                     for (int bj = 0; bj < 2; ++bj)
; #pragma unroll
;                         for (int n = 0; n < 2; ++n) {
;                             const f32x4 o = b[pc & 1][mm][bj][n] + acc[ai][bj][m][n] * scale;
;                             *(f32x4*)(out + off + bj * HALF + n * 16) = o;
;                             if (NORM) { s += (o[0] * o[0] + o[1] * o[1]) + (o[2] * o[2] + o[3] * o[3]);
;                                 u32x2 w; w.x = cvt_pk_bf16(o[0], o[1]); w.y = cvt_pk_bf16(o[2], o[3]); *(u32x2*)(xb + off + bj * HALF + n * 16) = w; }
;                         }
;                     if (NORM) { s += __shfl_xor(s, 16); s += __shfl_xor(s, 32); ssq[(size_t)row * 32 + u.pn * 4 + wc] = s; }
	v_pk_add_f32 v[12:13], v[12:13], v[180:181]
	v_pk_add_f32 v[14:15], v[14:15], v[182:183]
	s_waitcnt vmcnt(20)
	v_pk_add_f32 v[4:5], v[4:5], v[184:185]
	v_pk_add_f32 v[6:7], v[6:7], v[186:187]
	s_waitcnt vmcnt(19)
	v_pk_add_f32 v[8:9], v[8:9], v[208:209]
	v_pk_add_f32 v[10:11], v[10:11], v[210:211]
	s_waitcnt vmcnt(18)
	v_pk_add_f32 v[0:1], v[0:1], v[212:213]
	v_pk_add_f32 v[2:3], v[2:3], v[214:215]
	global_store_dwordx4 v220, v[28:31], s[88:89]
	global_store_dwordx4 v220, v[20:23], s[88:89] offset:512
	global_store_dwordx4 v221, v[24:27], s[88:89]
	global_store_dwordx4 v221, v[16:19], s[88:89] offset:512
	global_store_dwordx4 v222, v[12:15], s[88:89]
	global_store_dwordx4 v222, v[4:7], s[88:89] offset:512
	global_store_dwordx4 v223, v[8:11], s[88:89]
	global_store_dwordx4 v223, v[0:3], s[88:89] offset:512
	v_mul_f32_e32 v235, v28, v28
	v_fmac_f32_e32 v235, v29, v29
	v_fmac_f32_e32 v235, v30, v30
	v_fmac_f32_e32 v235, v31, v31
	v_fmac_f32_e32 v235, v20, v20
	v_fmac_f32_e32 v235, v21, v21
	v_fmac_f32_e32 v235, v22, v22
	v_fmac_f32_e32 v235, v23, v23
	v_mul_f32_e32 v236, v24, v24
	v_fmac_f32_e32 v236, v25, v25
	v_fmac_f32_e32 v236, v26, v26
	v_fmac_f32_e32 v236, v27, v27
	v_fmac_f32_e32 v236, v16, v16
	v_fmac_f32_e32 v236, v17, v17
	v_fmac_f32_e32 v236, v18, v18
	v_fmac_f32_e32 v236, v19, v19
	v_mul_f32_e32 v237, v12, v12
	v_fmac_f32_e32 v237, v13, v13
	v_fmac_f32_e32 v237, v14, v14
	v_fmac_f32_e32 v237, v15, v15
	v_fmac_f32_e32 v237, v4, v4
	v_fmac_f32_e32 v237, v5, v5
	v_fmac_f32_e32 v237, v6, v6
	v_fmac_f32_e32 v237, v7, v7
	v_mul_f32_e32 v238, v8, v8
	v_fmac_f32_e32 v238, v9, v9
	v_fmac_f32_e32 v238, v10, v10
	v_fmac_f32_e32 v238, v11, v11
	v_fmac_f32_e32 v238, v0, v0
	v_fmac_f32_e32 v238, v1, v1
	v_fmac_f32_e32 v238, v2, v2
	v_fmac_f32_e32 v238, v3, v3
	v_cvt_pk_bf16_f32 v164, v28, v29
	v_cvt_pk_bf16_f32 v165, v30, v31
	v_cvt_pk_bf16_f32 v168, v20, v21
	v_cvt_pk_bf16_f32 v169, v22, v23
	v_cvt_pk_bf16_f32 v172, v24, v25
	v_cvt_pk_bf16_f32 v173, v26, v27
	v_cvt_pk_bf16_f32 v176, v16, v17
	v_cvt_pk_bf16_f32 v177, v18, v19
	v_cvt_pk_bf16_f32 v180, v12, v13
	v_cvt_pk_bf16_f32 v181, v14, v15
	v_cvt_pk_bf16_f32 v184, v4, v5
	v_cvt_pk_bf16_f32 v185, v6, v7
	v_cvt_pk_bf16_f32 v208, v8, v9
	v_cvt_pk_bf16_f32 v209, v10, v11
	v_cvt_pk_bf16_f32 v212, v0, v1
	v_cvt_pk_bf16_f32 v213, v2, v3
	v_add_u32_e32 v239, 0xa0000, v234
	v_add_u32_e32 v190, 0xa8000, v234
	v_add_u32_e32 v191, 0xb0000, v234
	v_add_u32_e32 v192, 0xb8000, v234
	global_store_dwordx2 v239, v[164:165], s[44:45]
	global_store_dwordx2 v239, v[168:169], s[44:45] offset:256
	global_store_dwordx2 v190, v[172:173], s[44:45]
	global_store_dwordx2 v190, v[176:177], s[44:45] offset:256
	global_store_dwordx2 v191, v[180:181], s[44:45]
	global_store_dwordx2 v191, v[184:185], s[44:45] offset:256
	global_store_dwordx2 v192, v[208:209], s[44:45]
	global_store_dwordx2 v192, v[212:213], s[44:45] offset:256
	ds_bpermute_b32 v193, v230, v235
	ds_bpermute_b32 v194, v230, v236
	ds_bpermute_b32 v195, v230, v237
	ds_bpermute_b32 v207, v230, v238
	s_waitcnt lgkmcnt(0)
	v_add_f32_e32 v235, v235, v193
	v_add_f32_e32 v236, v236, v194
	v_add_f32_e32 v237, v237, v195
	v_add_f32_e32 v238, v238, v207
	ds_bpermute_b32 v193, v231, v235
	ds_bpermute_b32 v194, v231, v236
	ds_bpermute_b32 v195, v231, v237
	ds_bpermute_b32 v207, v231, v238
	s_waitcnt lgkmcnt(0)
	v_add_f32_e32 v235, v235, v193
	v_add_f32_e32 v236, v236, v194
	v_add_f32_e32 v237, v237, v195
	v_add_f32_e32 v238, v238, v207
	s_nop 1
	v_add_f32_dpp v193, v235, v235 row_ror:8 row_mask:0xf bank_mask:0xf
	v_add_f32_dpp v194, v236, v236 row_ror:8 row_mask:0xf bank_mask:0xf
	v_add_f32_dpp v195, v237, v237 row_ror:8 row_mask:0xf bank_mask:0xf
	v_add_f32_dpp v207, v238, v238 row_ror:8 row_mask:0xf bank_mask:0xf
	v_cndmask_b32_e64 v248, v193, v194, s[6:7]
	v_add_u32_e32 v250, 0x5000, v232
	v_cndmask_b32_e64 v249, v195, v207, s[6:7]
	v_add_u32_e32 v251, 0x5800, v232
	global_store_dword v250, v248, s[46:47]
	global_store_dword v251, v249, s[46:47]
	s_lshl_b32 s6, s55, 2
	s_ashr_i32 s7, s6, 31
	s_lshl_b64 s[6:7], s[6:7], 2
	s_cbranch_vccnz .LBB0_573
	s_andn2_b64 vcc, exec, s[10:11]
	s_cbranch_vccnz .LBB0_572
	s_barrier
	s_branch .LBB0_572

;     __device__ __forceinline__ void operator()(const f32x4 (&acc)[2][2][4][2], const Unit& u, int wr, int wc, int fr, int fq) const {
;         int row0 = u.pm * BM + wr * 64 + fr, col0 = u.pn * BM + wc * 32 + 4 * fq;
;         asm volatile("" : "+v"(row0), "+v"(col0));
.LBB0_736:
	s_and_b64 vcc, exec, s[0:1]
	s_mov_b64 s[0:1], -1
	v_bfe_u32 v225, v140, 3, 1
	v_and_b32_e32 v226, 0x77, v140
	v_lshl_add_u32 v227, v225, 4, v141
	v_lshl_add_u32 v223, s49, 8, v226
	v_lshl_or_b32 v224, s50, 8, v227
	v_lshlrev_b32_e32 v222, 13, v223
	v_lshl_add_u32 v222, v224, 2, v222
	s_nop 7
	v_mov_b32_e32 v244, v104
	v_mov_b32_e32 v245, v105
	v_mov_b32_e32 v246, v106
	v_mov_b32_e32 v247, v107
	v_mov_b32_dpp v104, v108 row_ror:8 row_mask:0xf bank_mask:0x3
	v_mov_b32_dpp v105, v109 row_ror:8 row_mask:0xf bank_mask:0x3
	v_mov_b32_dpp v106, v110 row_ror:8 row_mask:0xf bank_mask:0x3
	v_mov_b32_dpp v107, v111 row_ror:8 row_mask:0xf bank_mask:0x3
	v_mov_b32_dpp v108, v244 row_ror:8 row_mask:0xf bank_mask:0xc
	v_mov_b32_dpp v109, v245 row_ror:8 row_mask:0xf bank_mask:0xc
	v_mov_b32_dpp v110, v246 row_ror:8 row_mask:0xf bank_mask:0xc
	v_mov_b32_dpp v111, v247 row_ror:8 row_mask:0xf bank_mask:0xc
	v_mov_b32_e32 v244, v120
	v_mov_b32_e32 v245, v121
	v_mov_b32_e32 v246, v122
	v_mov_b32_e32 v247, v123
	v_mov_b32_dpp v120, v124 row_ror:8 row_mask:0xf bank_mask:0x3
	v_mov_b32_dpp v121, v125 row_ror:8 row_mask:0xf bank_mask:0x3
	v_mov_b32_dpp v122, v126 row_ror:8 row_mask:0xf bank_mask:0x3
	v_mov_b32_dpp v123, v127 row_ror:8 row_mask:0xf bank_mask:0x3
	v_mov_b32_dpp v124, v244 row_ror:8 row_mask:0xf bank_mask:0xc
	v_mov_b32_dpp v125, v245 row_ror:8 row_mask:0xf bank_mask:0xc
	v_mov_b32_dpp v126, v246 row_ror:8 row_mask:0xf bank_mask:0xc
	v_mov_b32_dpp v127, v247 row_ror:8 row_mask:0xf bank_mask:0xc
	v_mov_b32_e32 v244, v96
	v_mov_b32_e32 v245, v97
	v_mov_b32_e32 v246, v98
	v_mov_b32_e32 v247, v99
	v_mov_b32_dpp v96, v100 row_ror:8 row_mask:0xf bank_mask:0x3
	v_mov_b32_dpp v97, v101 row_ror:8 row_mask:0xf bank_mask:0x3
	v_mov_b32_dpp v98, v102 row_ror:8 row_mask:0xf bank_mask:0x3
	v_mov_b32_dpp v99, v103 row_ror:8 row_mask:0xf bank_mask:0x3
	v_mov_b32_dpp v100, v244 row_ror:8 row_mask:0xf bank_mask:0xc
	v_mov_b32_dpp v101, v245 row_ror:8 row_mask:0xf bank_mask:0xc
	v_mov_b32_dpp v102, v246 row_ror:8 row_mask:0xf bank_mask:0xc
	v_mov_b32_dpp v103, v247 row_ror:8 row_mask:0xf bank_mask:0xc
	v_mov_b32_e32 v244, v112
	v_mov_b32_e32 v245, v113
	v_mov_b32_e32 v246, v114
	v_mov_b32_e32 v247, v115
	v_mov_b32_dpp v112, v116 row_ror:8 row_mask:0xf bank_mask:0x3
	v_mov_b32_dpp v113, v117 row_ror:8 row_mask:0xf bank_mask:0x3
	v_mov_b32_dpp v114, v118 row_ror:8 row_mask:0xf bank_mask:0x3
	v_mov_b32_dpp v115, v119 row_ror:8 row_mask:0xf bank_mask:0x3
	v_mov_b32_dpp v116, v244 row_ror:8 row_mask:0xf bank_mask:0xc
	v_mov_b32_dpp v117, v245 row_ror:8 row_mask:0xf bank_mask:0xc
	v_mov_b32_dpp v118, v246 row_ror:8 row_mask:0xf bank_mask:0xc
	v_mov_b32_dpp v119, v247 row_ror:8 row_mask:0xf bank_mask:0xc
	v_mov_b32_e32 v244, v84
	v_mov_b32_e32 v245, v85
	v_mov_b32_e32 v246, v86
	v_mov_b32_e32 v247, v87
	v_mov_b32_dpp v84, v92 row_ror:8 row_mask:0xf bank_mask:0x3
	v_mov_b32_dpp v85, v93 row_ror:8 row_mask:0xf bank_mask:0x3
	v_mov_b32_dpp v86, v94 row_ror:8 row_mask:0xf bank_mask:0x3
	v_mov_b32_dpp v87, v95 row_ror:8 row_mask:0xf bank_mask:0x3
	v_mov_b32_dpp v92, v244 row_ror:8 row_mask:0xf bank_mask:0xc
	v_mov_b32_dpp v93, v245 row_ror:8 row_mask:0xf bank_mask:0xc
	v_mov_b32_dpp v94, v246 row_ror:8 row_mask:0xf bank_mask:0xc
	v_mov_b32_dpp v95, v247 row_ror:8 row_mask:0xf bank_mask:0xc
	v_mov_b32_e32 v244, v80
	v_mov_b32_e32 v245, v81
	v_mov_b32_e32 v246, v82
	v_mov_b32_e32 v247, v83
	v_mov_b32_dpp v80, v88 row_ror:8 row_mask:0xf bank_mask:0x3
	v_mov_b32_dpp v81, v89 row_ror:8 row_mask:0xf bank_mask:0x3
	v_mov_b32_dpp v82, v90 row_ror:8 row_mask:0xf bank_mask:0x3
	v_mov_b32_dpp v83, v91 row_ror:8 row_mask:0xf bank_mask:0x3
	v_mov_b32_dpp v88, v244 row_ror:8 row_mask:0xf bank_mask:0xc
	v_mov_b32_dpp v89, v245 row_ror:8 row_mask:0xf bank_mask:0xc
	v_mov_b32_dpp v90, v246 row_ror:8 row_mask:0xf bank_mask:0xc
	v_mov_b32_dpp v91, v247 row_ror:8 row_mask:0xf bank_mask:0xc
	v_mov_b32_e32 v244, v68
	v_mov_b32_e32 v245, v69
	v_mov_b32_e32 v246, v70
	v_mov_b32_e32 v247, v71
	v_mov_b32_dpp v68, v76 row_ror:8 row_mask:0xf bank_mask:0x3
	v_mov_b32_dpp v69, v77 row_ror:8 row_mask:0xf bank_mask:0x3
	v_mov_b32_dpp v70, v78 row_ror:8 row_mask:0xf bank_mask:0x3
	v_mov_b32_dpp v71, v79 row_ror:8 row_mask:0xf bank_mask:0x3
	v_mov_b32_dpp v76, v244 row_ror:8 row_mask:0xf bank_mask:0xc
	v_mov_b32_dpp v77, v245 row_ror:8 row_mask:0xf bank_mask:0xc
	v_mov_b32_dpp v78, v246 row_ror:8 row_mask:0xf bank_mask:0xc
	v_mov_b32_dpp v79, v247 row_ror:8 row_mask:0xf bank_mask:0xc
	v_mov_b32_e32 v244, v64
	v_mov_b32_e32 v245, v65
	v_mov_b32_e32 v246, v66
	v_mov_b32_e32 v247, v67
	v_mov_b32_dpp v64, v72 row_ror:8 row_mask:0xf bank_mask:0x3
	v_mov_b32_dpp v65, v73 row_ror:8 row_mask:0xf bank_mask:0x3
	v_mov_b32_dpp v66, v74 row_ror:8 row_mask:0xf bank_mask:0x3
	v_mov_b32_dpp v67, v75 row_ror:8 row_mask:0xf bank_mask:0x3
	v_mov_b32_dpp v72, v244 row_ror:8 row_mask:0xf bank_mask:0xc
	v_mov_b32_dpp v73, v245 row_ror:8 row_mask:0xf bank_mask:0xc
	v_mov_b32_dpp v74, v246 row_ror:8 row_mask:0xf bank_mask:0xc
	v_mov_b32_dpp v75, v247 row_ror:8 row_mask:0xf bank_mask:0xc
	v_mov_b32_e32 v244, v40
	v_mov_b32_e32 v245, v41
	v_mov_b32_e32 v246, v42
	v_mov_b32_e32 v247, v43
	v_mov_b32_dpp v40, v44 row_ror:8 row_mask:0xf bank_mask:0x3
	v_mov_b32_dpp v41, v45 row_ror:8 row_mask:0xf bank_mask:0x3
	v_mov_b32_dpp v42, v46 row_ror:8 row_mask:0xf bank_mask:0x3
	v_mov_b32_dpp v43, v47 row_ror:8 row_mask:0xf bank_mask:0x3
	v_mov_b32_dpp v44, v244 row_ror:8 row_mask:0xf bank_mask:0xc
	v_mov_b32_dpp v45, v245 row_ror:8 row_mask:0xf bank_mask:0xc
	v_mov_b32_dpp v46, v246 row_ror:8 row_mask:0xf bank_mask:0xc
;     __device__ __forceinline__ void operator()(const f32x4 (&acc)[2][2][4][2], const Unit& u, int wr, int wc, int fr, int fq) const {
;     ...
;                 for (int mm = 0; mm < 2; ++mm) { const size_t off = (size_t)(row0 + (ch >> 1) * HALF + ((ch & 1) * 2 + mm) * 16) * ldc + col0;
; #pragma unroll
;                     for (int bj = 0; bj < 2; ++bj)
; #pragma unroll
;                         for (int n = 0; n < 2; ++n) b[ch & 1][mm][bj][n] = *(const f32x4*)(base + off + bj * HALF + n * 16); }
;             }
;             asm volatile("" ::: "memory");
;             if (ch > 0) {
;                 const int pc = ch - 1, ai = pc >> 1;
; #pragma unroll
;                 for (int mm = 0; mm < 2; ++mm) { const int m = (pc & 1) * 2 + mm, row = row0 + ai * HALF + m * 16; const size_t off = (size_t)row * ldc + col0;
;                     float s = 0.f;
; #pragma unroll
;                     for (int bj = 0; bj < 2; ++bj)
; #pragma unroll
;                         for (int n = 0; n < 2; ++n) {
;                             const f32x4 o = b[pc & 1][mm][bj][n] + acc[ai][bj][m][n] * scale;
	v_mov_b32_dpp v47, v247 row_ror:8 row_mask:0xf bank_mask:0xc
	v_mov_b32_e32 v244, v56
	v_mov_b32_e32 v245, v57
	v_mov_b32_e32 v246, v58
	v_mov_b32_e32 v247, v59
	v_mov_b32_dpp v56, v60 row_ror:8 row_mask:0xf bank_mask:0x3
	v_mov_b32_dpp v57, v61 row_ror:8 row_mask:0xf bank_mask:0x3
	v_mov_b32_dpp v58, v62 row_ror:8 row_mask:0xf bank_mask:0x3
	v_mov_b32_dpp v59, v63 row_ror:8 row_mask:0xf bank_mask:0x3
	v_mov_b32_dpp v60, v244 row_ror:8 row_mask:0xf bank_mask:0xc
	v_mov_b32_dpp v61, v245 row_ror:8 row_mask:0xf bank_mask:0xc
	v_mov_b32_dpp v62, v246 row_ror:8 row_mask:0xf bank_mask:0xc
	v_mov_b32_dpp v63, v247 row_ror:8 row_mask:0xf bank_mask:0xc
	v_mov_b32_e32 v244, v32
	v_mov_b32_e32 v245, v33
	v_mov_b32_e32 v246, v34
	v_mov_b32_e32 v247, v35
	v_mov_b32_dpp v32, v36 row_ror:8 row_mask:0xf bank_mask:0x3
	v_mov_b32_dpp v33, v37 row_ror:8 row_mask:0xf bank_mask:0x3
	v_mov_b32_dpp v34, v38 row_ror:8 row_mask:0xf bank_mask:0x3
	v_mov_b32_dpp v35, v39 row_ror:8 row_mask:0xf bank_mask:0x3
	v_mov_b32_dpp v36, v244 row_ror:8 row_mask:0xf bank_mask:0xc
	v_mov_b32_dpp v37, v245 row_ror:8 row_mask:0xf bank_mask:0xc
	v_mov_b32_dpp v38, v246 row_ror:8 row_mask:0xf bank_mask:0xc
	v_mov_b32_dpp v39, v247 row_ror:8 row_mask:0xf bank_mask:0xc
	v_mov_b32_e32 v244, v48
	v_mov_b32_e32 v245, v49
	v_mov_b32_e32 v246, v50
	v_mov_b32_e32 v247, v51
	v_mov_b32_dpp v48, v52 row_ror:8 row_mask:0xf bank_mask:0x3
	v_mov_b32_dpp v49, v53 row_ror:8 row_mask:0xf bank_mask:0x3
	v_mov_b32_dpp v50, v54 row_ror:8 row_mask:0xf bank_mask:0x3
	v_mov_b32_dpp v51, v55 row_ror:8 row_mask:0xf bank_mask:0x3
	v_mov_b32_dpp v52, v244 row_ror:8 row_mask:0xf bank_mask:0xc
	v_mov_b32_dpp v53, v245 row_ror:8 row_mask:0xf bank_mask:0xc
	v_mov_b32_dpp v54, v246 row_ror:8 row_mask:0xf bank_mask:0xc
	v_mov_b32_dpp v55, v247 row_ror:8 row_mask:0xf bank_mask:0xc
	v_mov_b32_e32 v244, v20
	v_mov_b32_e32 v245, v21
	v_mov_b32_e32 v246, v22
	v_mov_b32_e32 v247, v23
	v_mov_b32_dpp v20, v28 row_ror:8 row_mask:0xf bank_mask:0x3
	v_mov_b32_dpp v21, v29 row_ror:8 row_mask:0xf bank_mask:0x3
	v_mov_b32_dpp v22, v30 row_ror:8 row_mask:0xf bank_mask:0x3
	v_mov_b32_dpp v23, v31 row_ror:8 row_mask:0xf bank_mask:0x3
	v_mov_b32_dpp v28, v244 row_ror:8 row_mask:0xf bank_mask:0xc
	v_mov_b32_dpp v29, v245 row_ror:8 row_mask:0xf bank_mask:0xc
	v_mov_b32_dpp v30, v246 row_ror:8 row_mask:0xf bank_mask:0xc
	v_mov_b32_dpp v31, v247 row_ror:8 row_mask:0xf bank_mask:0xc
	v_mov_b32_e32 v244, v16
	v_mov_b32_e32 v245, v17
	v_mov_b32_e32 v246, v18
	v_mov_b32_e32 v247, v19
	v_mov_b32_dpp v16, v24 row_ror:8 row_mask:0xf bank_mask:0x3
	v_mov_b32_dpp v17, v25 row_ror:8 row_mask:0xf bank_mask:0x3
	v_mov_b32_dpp v18, v26 row_ror:8 row_mask:0xf bank_mask:0x3
	v_mov_b32_dpp v19, v27 row_ror:8 row_mask:0xf bank_mask:0x3
	v_mov_b32_dpp v24, v244 row_ror:8 row_mask:0xf bank_mask:0xc
	v_mov_b32_dpp v25, v245 row_ror:8 row_mask:0xf bank_mask:0xc
	v_mov_b32_dpp v26, v246 row_ror:8 row_mask:0xf bank_mask:0xc
	v_mov_b32_dpp v27, v247 row_ror:8 row_mask:0xf bank_mask:0xc
	v_mov_b32_e32 v244, v4
	v_mov_b32_e32 v245, v5
	v_mov_b32_e32 v246, v6
	v_mov_b32_e32 v247, v7
	v_mov_b32_dpp v4, v12 row_ror:8 row_mask:0xf bank_mask:0x3
	v_mov_b32_dpp v5, v13 row_ror:8 row_mask:0xf bank_mask:0x3
	v_mov_b32_dpp v6, v14 row_ror:8 row_mask:0xf bank_mask:0x3
	v_mov_b32_dpp v7, v15 row_ror:8 row_mask:0xf bank_mask:0x3
	v_mov_b32_dpp v12, v244 row_ror:8 row_mask:0xf bank_mask:0xc
	v_mov_b32_dpp v13, v245 row_ror:8 row_mask:0xf bank_mask:0xc
	v_mov_b32_dpp v14, v246 row_ror:8 row_mask:0xf bank_mask:0xc
	v_mov_b32_dpp v15, v247 row_ror:8 row_mask:0xf bank_mask:0xc
	v_mov_b32_e32 v244, v0
	v_mov_b32_e32 v245, v1
	v_mov_b32_e32 v246, v2
	v_mov_b32_e32 v247, v3
	v_mov_b32_dpp v0, v8 row_ror:8 row_mask:0xf bank_mask:0x3
	v_mov_b32_dpp v1, v9 row_ror:8 row_mask:0xf bank_mask:0x3
	v_mov_b32_dpp v2, v10 row_ror:8 row_mask:0xf bank_mask:0x3
	v_mov_b32_dpp v3, v11 row_ror:8 row_mask:0xf bank_mask:0x3
	v_mov_b32_dpp v8, v244 row_ror:8 row_mask:0xf bank_mask:0xc
	v_mov_b32_dpp v9, v245 row_ror:8 row_mask:0xf bank_mask:0xc
	v_mov_b32_dpp v10, v246 row_ror:8 row_mask:0xf bank_mask:0xc
	v_mov_b32_dpp v11, v247 row_ror:8 row_mask:0xf bank_mask:0xc
	v_add_u32_e32 v214, 0x0, v222
	v_add_u32_e32 v215, 0x10000, v222
	v_add_u32_e32 v216, 0x20000, v222
	v_add_u32_e32 v217, 0x30000, v222
	global_load_dwordx4 v[148:151], v214, s[88:89]
	global_load_dwordx4 v[152:155], v214, s[88:89] offset:512
	global_load_dwordx4 v[156:159], v215, s[88:89]
	global_load_dwordx4 v[160:163], v215, s[88:89] offset:512
	global_load_dwordx4 v[164:167], v216, s[88:89]
	global_load_dwordx4 v[168:171], v216, s[88:89] offset:512
	global_load_dwordx4 v[172:175], v217, s[88:89]
	global_load_dwordx4 v[176:179], v217, s[88:89] offset:512
	v_add_u32_e32 v218, 0x40000, v222
	v_add_u32_e32 v219, 0x50000, v222
	v_add_u32_e32 v220, 0x60000, v222
	v_add_u32_e32 v221, 0x70000, v222
	global_load_dwordx4 v[180:183], v218, s[88:89]
	global_load_dwordx4 v[184:187], v218, s[88:89] offset:512
	global_load_dwordx4 v[190:193], v219, s[88:89]
	global_load_dwordx4 v[194:197], v219, s[88:89] offset:512
	global_load_dwordx4 v[198:201], v220, s[88:89]
	global_load_dwordx4 v[202:205], v220, s[88:89] offset:512
	global_load_dwordx4 v[206:209], v221, s[88:89]
	global_load_dwordx4 v[210:213], v221, s[88:89] offset:512
	s_waitcnt vmcnt(15)
	v_pk_fma_f32 v[108:109], v[108:109], 0.5, v[148:149] op_sel_hi:[1,0,1]
	v_pk_fma_f32 v[110:111], v[110:111], 0.5, v[150:151] op_sel_hi:[1,0,1]
	s_waitcnt vmcnt(14)
	v_pk_fma_f32 v[124:125], v[124:125], 0.5, v[152:153] op_sel_hi:[1,0,1]
	v_pk_fma_f32 v[126:127], v[126:127], 0.5, v[154:155] op_sel_hi:[1,0,1]
	s_waitcnt vmcnt(13)
;     __device__ __forceinline__ void operator()(const f32x4 (&acc)[2][2][4][2], const Unit& u, int wr, int wc, int fr, int fq) const {
;     ...
;                 for (int mm = 0; mm < 2; ++mm) { const size_t off = (size_t)(row0 + (ch >> 1) * HALF + ((ch & 1) * 2 + mm) * 16) * ldc + col0;
; #pragma unroll
;                     for (int bj = 0; bj < 2; ++bj)
; #pragma unroll
;                         for (int n = 0; n < 2; ++n) b[ch & 1][mm][bj][n] = *(const f32x4*)(base + off + bj * HALF + n * 16); }
;             }
;             asm volatile("" ::: "memory");
;             if (ch > 0) {
;                 const int pc = ch - 1, ai = pc >> 1;
; #pragma unroll
;                 for (int mm = 0; mm < 2; ++mm) { const int m = (pc & 1) * 2 + mm, row = row0 + ai * HALF + m * 16; const size_t off = (size_t)row * ldc + col0;
;                     float s = 0.f;
; #pragma unroll
;                     for (int bj = 0; bj < 2; ++bj)
; #pragma unroll
;                         for (int n = 0; n < 2; ++n) {
;                             const f32x4 o = b[pc & 1][mm][bj][n] + acc[ai][bj][m][n] * scale;
;                             *(f32x4*)(out + off + bj * HALF + n * 16) = o;
	v_pk_fma_f32 v[104:105], v[104:105], 0.5, v[156:157] op_sel_hi:[1,0,1]
	v_pk_fma_f32 v[106:107], v[106:107], 0.5, v[158:159] op_sel_hi:[1,0,1]
	s_waitcnt vmcnt(12)
	v_pk_fma_f32 v[120:121], v[120:121], 0.5, v[160:161] op_sel_hi:[1,0,1]
	v_pk_fma_f32 v[122:123], v[122:123], 0.5, v[162:163] op_sel_hi:[1,0,1]
	s_waitcnt vmcnt(11)
	v_pk_fma_f32 v[100:101], v[100:101], 0.5, v[164:165] op_sel_hi:[1,0,1]
	v_pk_fma_f32 v[102:103], v[102:103], 0.5, v[166:167] op_sel_hi:[1,0,1]
	s_waitcnt vmcnt(10)
	v_pk_fma_f32 v[116:117], v[116:117], 0.5, v[168:169] op_sel_hi:[1,0,1]
	v_pk_fma_f32 v[118:119], v[118:119], 0.5, v[170:171] op_sel_hi:[1,0,1]
	s_waitcnt vmcnt(9)
	v_pk_fma_f32 v[96:97], v[96:97], 0.5, v[172:173] op_sel_hi:[1,0,1]
	v_pk_fma_f32 v[98:99], v[98:99], 0.5, v[174:175] op_sel_hi:[1,0,1]
	s_waitcnt vmcnt(8)
	v_pk_fma_f32 v[112:113], v[112:113], 0.5, v[176:177] op_sel_hi:[1,0,1]
	v_pk_fma_f32 v[114:115], v[114:115], 0.5, v[178:179] op_sel_hi:[1,0,1]
	global_store_dwordx4 v214, v[108:111], s[88:89]
	global_store_dwordx4 v214, v[124:127], s[88:89] offset:512
	global_store_dwordx4 v215, v[104:107], s[88:89]
	global_store_dwordx4 v215, v[120:123], s[88:89] offset:512
	global_store_dwordx4 v216, v[100:103], s[88:89]
	global_store_dwordx4 v216, v[116:119], s[88:89] offset:512
	global_store_dwordx4 v217, v[96:99], s[88:89]
	global_store_dwordx4 v217, v[112:115], s[88:89] offset:512
	v_add_u32_e32 v214, 0x100000, v222
	v_add_u32_e32 v215, 0x110000, v222
	v_add_u32_e32 v216, 0x120000, v222
	v_add_u32_e32 v217, 0x130000, v222
	global_load_dwordx4 v[148:151], v214, s[88:89]
	global_load_dwordx4 v[152:155], v214, s[88:89] offset:512
	global_load_dwordx4 v[156:159], v215, s[88:89]
	global_load_dwordx4 v[160:163], v215, s[88:89] offset:512
	global_load_dwordx4 v[164:167], v216, s[88:89]
	global_load_dwordx4 v[168:171], v216, s[88:89] offset:512
	global_load_dwordx4 v[172:175], v217, s[88:89]
	global_load_dwordx4 v[176:179], v217, s[88:89] offset:512
	s_waitcnt vmcnt(23)
	v_pk_fma_f32 v[92:93], v[92:93], 0.5, v[180:181] op_sel_hi:[1,0,1]
	v_pk_fma_f32 v[94:95], v[94:95], 0.5, v[182:183] op_sel_hi:[1,0,1]
	s_waitcnt vmcnt(22)
	v_pk_fma_f32 v[88:89], v[88:89], 0.5, v[184:185] op_sel_hi:[1,0,1]
	v_pk_fma_f32 v[90:91], v[90:91], 0.5, v[186:187] op_sel_hi:[1,0,1]
	s_waitcnt vmcnt(21)
	v_pk_fma_f32 v[84:85], v[84:85], 0.5, v[190:191] op_sel_hi:[1,0,1]
	v_pk_fma_f32 v[86:87], v[86:87], 0.5, v[192:193] op_sel_hi:[1,0,1]
	s_waitcnt vmcnt(20)
	v_pk_fma_f32 v[80:81], v[80:81], 0.5, v[194:195] op_sel_hi:[1,0,1]
	v_pk_fma_f32 v[82:83], v[82:83], 0.5, v[196:197] op_sel_hi:[1,0,1]
	s_waitcnt vmcnt(19)
	v_pk_fma_f32 v[76:77], v[76:77], 0.5, v[198:199] op_sel_hi:[1,0,1]
	v_pk_fma_f32 v[78:79], v[78:79], 0.5, v[200:201] op_sel_hi:[1,0,1]
	s_waitcnt vmcnt(18)
	v_pk_fma_f32 v[72:73], v[72:73], 0.5, v[202:203] op_sel_hi:[1,0,1]
	v_pk_fma_f32 v[74:75], v[74:75], 0.5, v[204:205] op_sel_hi:[1,0,1]
	s_waitcnt vmcnt(17)
	v_pk_fma_f32 v[68:69], v[68:69], 0.5, v[206:207] op_sel_hi:[1,0,1]
	v_pk_fma_f32 v[70:71], v[70:71], 0.5, v[208:209] op_sel_hi:[1,0,1]
	s_waitcnt vmcnt(16)
	v_pk_fma_f32 v[64:65], v[64:65], 0.5, v[210:211] op_sel_hi:[1,0,1]
	v_pk_fma_f32 v[66:67], v[66:67], 0.5, v[212:213] op_sel_hi:[1,0,1]
	global_store_dwordx4 v218, v[92:95], s[88:89]
	global_store_dwordx4 v218, v[88:91], s[88:89] offset:512
	global_store_dwordx4 v219, v[84:87], s[88:89]
	global_store_dwordx4 v219, v[80:83], s[88:89] offset:512
	global_store_dwordx4 v220, v[76:79], s[88:89]
	global_store_dwordx4 v220, v[72:75], s[88:89] offset:512
	global_store_dwordx4 v221, v[68:71], s[88:89]
	global_store_dwordx4 v221, v[64:67], s[88:89] offset:512
	v_add_u32_e32 v218, 0x140000, v222
	v_add_u32_e32 v219, 0x150000, v222
	v_add_u32_e32 v220, 0x160000, v222
	v_add_u32_e32 v221, 0x170000, v222
	global_load_dwordx4 v[180:183], v218, s[88:89]
	global_load_dwordx4 v[184:187], v218, s[88:89] offset:512
	global_load_dwordx4 v[190:193], v219, s[88:89]
	global_load_dwordx4 v[194:197], v219, s[88:89] offset:512
	global_load_dwordx4 v[198:201], v220, s[88:89]
	global_load_dwordx4 v[202:205], v220, s[88:89] offset:512
	global_load_dwordx4 v[206:209], v221, s[88:89]
	global_load_dwordx4 v[210:213], v221, s[88:89] offset:512
	s_waitcnt vmcnt(23)
; #define PG8_BAR __builtin_amdgcn_s_barrier()
; template <class Epi, class Sched, bool ALIGN_EPI = false, bool SP2 = false>
; __device__ __forceinline__ void gemm_phase(PG8_LAS unsigned char* lds, const Gemm g, const Sched& S, const Epi& E) {
;     ...
;         if constexpr (!Epi::AFTER_DRAIN) { E(acc, cur, wr, wc, fr, fq); S.done(cur); }
;         if (!has_next) break;
;         cur = nxt; cA = nA; cB = nB; ++ui;
;         if constexpr (ALIGN_EPI) { if (wr == 1) PG8_BAR; }
;     __device__ __forceinline__ void operator()(const f32x4 (&acc)[2][2][4][2], const Unit& u, int wr, int wc, int fr, int fq) const {
;     ...
;                 for (int mm = 0; mm < 2; ++mm) { const size_t off = (size_t)(row0 + (ch >> 1) * HALF + ((ch & 1) * 2 + mm) * 16) * ldc + col0;
; #pragma unroll
;                     for (int bj = 0; bj < 2; ++bj)
; #pragma unroll
;                         for (int n = 0; n < 2; ++n) b[ch & 1][mm][bj][n] = *(const f32x4*)(base + off + bj * HALF + n * 16); }
;             }
;             asm volatile("" ::: "memory");
;             if (ch > 0) {
;                 const int pc = ch - 1, ai = pc >> 1;
; #pragma unroll
;                 for (int mm = 0; mm < 2; ++mm) { const int m = (pc & 1) * 2 + mm, row = row0 + ai * HALF + m * 16; const size_t off = (size_t)row * ldc + col0;
;                     float s = 0.f;
; #pragma unroll
;                     for (int bj = 0; bj < 2; ++bj)
; #pragma unroll
;                         for (int n = 0; n < 2; ++n) {
;                             const f32x4 o = b[pc & 1][mm][bj][n] + acc[ai][bj][m][n] * scale;
;                             *(f32x4*)(out + off + bj * HALF + n * 16) = o;
	v_pk_fma_f32 v[44:45], v[44:45], 0.5, v[148:149] op_sel_hi:[1,0,1]
	v_pk_fma_f32 v[46:47], v[46:47], 0.5, v[150:151] op_sel_hi:[1,0,1]
	s_waitcnt vmcnt(22)
	v_pk_fma_f32 v[60:61], v[60:61], 0.5, v[152:153] op_sel_hi:[1,0,1]
	v_pk_fma_f32 v[62:63], v[62:63], 0.5, v[154:155] op_sel_hi:[1,0,1]
	s_waitcnt vmcnt(21)
	v_pk_fma_f32 v[40:41], v[40:41], 0.5, v[156:157] op_sel_hi:[1,0,1]
	v_pk_fma_f32 v[42:43], v[42:43], 0.5, v[158:159] op_sel_hi:[1,0,1]
	s_waitcnt vmcnt(20)
	v_pk_fma_f32 v[56:57], v[56:57], 0.5, v[160:161] op_sel_hi:[1,0,1]
	v_pk_fma_f32 v[58:59], v[58:59], 0.5, v[162:163] op_sel_hi:[1,0,1]
	s_waitcnt vmcnt(19)
	v_pk_fma_f32 v[36:37], v[36:37], 0.5, v[164:165] op_sel_hi:[1,0,1]
	v_pk_fma_f32 v[38:39], v[38:39], 0.5, v[166:167] op_sel_hi:[1,0,1]
	s_waitcnt vmcnt(18)
	v_pk_fma_f32 v[52:53], v[52:53], 0.5, v[168:169] op_sel_hi:[1,0,1]
	v_pk_fma_f32 v[54:55], v[54:55], 0.5, v[170:171] op_sel_hi:[1,0,1]
	s_waitcnt vmcnt(17)
	v_pk_fma_f32 v[32:33], v[32:33], 0.5, v[172:173] op_sel_hi:[1,0,1]
	v_pk_fma_f32 v[34:35], v[34:35], 0.5, v[174:175] op_sel_hi:[1,0,1]
	s_waitcnt vmcnt(16)
	v_pk_fma_f32 v[48:49], v[48:49], 0.5, v[176:177] op_sel_hi:[1,0,1]
	v_pk_fma_f32 v[50:51], v[50:51], 0.5, v[178:179] op_sel_hi:[1,0,1]
	global_store_dwordx4 v214, v[44:47], s[88:89]
	global_store_dwordx4 v214, v[60:63], s[88:89] offset:512
	global_store_dwordx4 v215, v[40:43], s[88:89]
	global_store_dwordx4 v215, v[56:59], s[88:89] offset:512
	global_store_dwordx4 v216, v[36:39], s[88:89]
	global_store_dwordx4 v216, v[52:55], s[88:89] offset:512
	global_store_dwordx4 v217, v[32:35], s[88:89]
	global_store_dwordx4 v217, v[48:51], s[88:89] offset:512
	s_waitcnt vmcnt(15)
	v_pk_fma_f32 v[28:29], v[28:29], 0.5, v[180:181] op_sel_hi:[1,0,1]
	v_pk_fma_f32 v[30:31], v[30:31], 0.5, v[182:183] op_sel_hi:[1,0,1]
	s_waitcnt vmcnt(14)
	v_pk_fma_f32 v[24:25], v[24:25], 0.5, v[184:185] op_sel_hi:[1,0,1]
	v_pk_fma_f32 v[26:27], v[26:27], 0.5, v[186:187] op_sel_hi:[1,0,1]
	s_waitcnt vmcnt(13)
	v_pk_fma_f32 v[20:21], v[20:21], 0.5, v[190:191] op_sel_hi:[1,0,1]
	v_pk_fma_f32 v[22:23], v[22:23], 0.5, v[192:193] op_sel_hi:[1,0,1]
	s_waitcnt vmcnt(12)
	v_pk_fma_f32 v[16:17], v[16:17], 0.5, v[194:195] op_sel_hi:[1,0,1]
	v_pk_fma_f32 v[18:19], v[18:19], 0.5, v[196:197] op_sel_hi:[1,0,1]
	s_waitcnt vmcnt(11)
	v_pk_fma_f32 v[12:13], v[12:13], 0.5, v[198:199] op_sel_hi:[1,0,1]
	v_pk_fma_f32 v[14:15], v[14:15], 0.5, v[200:201] op_sel_hi:[1,0,1]
	s_waitcnt vmcnt(10)
	v_pk_fma_f32 v[8:9], v[8:9], 0.5, v[202:203] op_sel_hi:[1,0,1]
	v_pk_fma_f32 v[10:11], v[10:11], 0.5, v[204:205] op_sel_hi:[1,0,1]
	s_waitcnt vmcnt(9)
	v_pk_fma_f32 v[4:5], v[4:5], 0.5, v[206:207] op_sel_hi:[1,0,1]
	v_pk_fma_f32 v[6:7], v[6:7], 0.5, v[208:209] op_sel_hi:[1,0,1]
	s_waitcnt vmcnt(8)
	v_pk_fma_f32 v[0:1], v[0:1], 0.5, v[210:211] op_sel_hi:[1,0,1]
	v_pk_fma_f32 v[2:3], v[2:3], 0.5, v[212:213] op_sel_hi:[1,0,1]
	global_store_dwordx4 v218, v[28:31], s[88:89]
	global_store_dwordx4 v218, v[24:27], s[88:89] offset:512
	global_store_dwordx4 v219, v[20:23], s[88:89]
	global_store_dwordx4 v219, v[16:19], s[88:89] offset:512
	global_store_dwordx4 v220, v[12:15], s[88:89]
	global_store_dwordx4 v220, v[8:11], s[88:89] offset:512
	global_store_dwordx4 v221, v[4:7], s[88:89]
	global_store_dwordx4 v221, v[0:3], s[88:89] offset:512
	s_cbranch_vccnz .LBB0_721
	s_andn2_b64 vcc, exec, s[12:13]
	s_cbranch_vccnz .LBB0_720
	s_barrier
	s_branch .LBB0_720
